# layer-1 g1/sh2/sc2/g2 modulation columns moved from the prologue to idle workgroups of layer 1's GLU GEMM (pipelined GEMV); weight-conversion loop of the idle GEMM slots hand-written with 3 items' loa
# speedup vs baseline: 1.0096x; 1.0096x over previous
.Lmod_host:
	s_cmpk_lg_i32 s14, 0x100
	s_cbranch_scc1 .LBB0_140
	s_cmpk_lt_i32 s2, 0xc0
	s_cbranch_scc1 .LBB0_140
	s_lshl_b32 s0, s43, 14
	s_add_i32 s34, s0, 0
	s_sub_i32 s12, s2, 64
	s_lshl_b32 s12, s12, 3
	s_add_i32 s12, s12, s43
	s_mov_b32 s1, 0
	s_branch .LBB0_474

.Lconv_entry:
	s_add_i32 s25, s25, s4
	s_cmp_ge_i32 s25, s39
	s_cbranch_scc1 .LBB0_219
	v_lshrrev_b32_e32 v5, 5, v168
	v_and_b32_e32 v6, 31, v168
	v_lshrrev_b32_e32 v7, 3, v168
	v_and_b32_e32 v8, 7, v168
	s_lshl_b32 s4, s43, 14
	v_mul_u32_u24_e32 v9, 33, v5
	v_mul_u32_u24_e32 v10, 0x108, v8
	v_add_u32_e32 v9, v9, v6
	v_add_u32_e32 v10, v10, v7
	v_lshl_add_u32 v9, v9, 2, s4
	v_lshl_add_u32 v10, v10, 2, s4
	v_lshlrev_b32_e32 v6, 2, v6
	v_lshlrev_b32_e32 v8, 4, v8
	s_movk_i32 s4, 0x5c00
	s_cmp_ge_u32 s25, s4
	s_cselect_b32 s0, 1, 0
	s_cselect_b32 s5, s4, 0
	s_sub_u32 s3, s25, s5
	s_cmpk_lt_u32 s3, 0x1000
	s_cbranch_scc1 .LitA_p1k0
	s_cmpk_lt_u32 s3, 0x1200
	s_cbranch_scc1 .LitA_p1k1
	s_cmpk_lt_u32 s3, 0x1a00
	s_cbranch_scc1 .LitA_p1k2
	s_cmpk_lt_u32 s3, 0x4600
	s_cbranch_scc1 .LitA_p1k3
	s_load_dwordx2 s[8:9], s[58:59], 0xc0
	s_sub_u32 s3, s3, 0x4600
	s_lshr_b32 s4, s3, 6
	s_and_b32 s5, s3, 63
	s_mul_i32 s6, s0, 0x2c00000
	s_lshl_b32 s7, s4, 19
	s_add_u32 s6, s6, s7
	s_lshl_b32 s7, s5, 7
	s_add_u32 s6, s6, s7
	s_mul_i32 s7, s0, 0x1600000
	s_add_u32 s7, s7, 0x9c00000
	s_mul_i32 s5, s5, 0x58000
	s_add_u32 s7, s7, s5
	s_lshl_b32 s4, s4, 7
	s_add_u32 s7, s7, s4
	s_movk_i32 s12, 0x4000
	s_mov_b32 s13, 0x16000
	s_branch .LitA_p1c
.LitA_p1k0:
	s_load_dwordx2 s[8:9], s[58:59], 0x40
	s_lshr_b32 s4, s3, 7
	s_and_b32 s5, s3, 127
	s_mul_i32 s6, s0, 0x2000000
	s_lshl_b32 s7, s4, 20
	s_add_u32 s6, s6, s7
	s_lshl_b32 s7, s5, 7
	s_add_u32 s6, s6, s7
	s_mul_i32 s7, s0, 0x1000000
	s_add_u32 s7, s7, 0x1000000
	s_lshl_b32 s5, s5, 17
	s_add_u32 s7, s7, s5
	s_lshl_b32 s4, s4, 7
	s_add_u32 s7, s7, s4
	s_mov_b32 s12, 0x8000
	s_mov_b32 s13, 0x8000
	s_branch .LitA_p1c
.LitA_p1k1:
	s_load_dwordx2 s[8:9], s[58:59], 0x88
	s_sub_u32 s3, s3, 0x1000
	s_lshr_b32 s4, s3, 5
	s_and_b32 s5, s3, 31
	s_mul_i32 s6, s0, 0x400000
	s_lshl_b32 s7, s4, 18
	s_add_u32 s6, s6, s7
	s_lshl_b32 s7, s5, 7
	s_add_u32 s6, s6, s7
	s_mul_i32 s7, s0, 0x200000
	s_add_u32 s7, s7, 0x3000000
	s_lshl_b32 s5, s5, 16
	s_add_u32 s7, s7, s5
	s_lshl_b32 s4, s4, 7
	s_add_u32 s7, s7, s4
	s_movk_i32 s12, 0x2000
	s_movk_i32 s13, 0x4000
	s_branch .LitA_p1c
.LitA_p1k2:
	s_load_dwordx2 s[8:9], s[58:59], 0xa0
	s_sub_u32 s3, s3, 0x1200
	s_lshr_b32 s4, s3, 6
	s_and_b32 s5, s3, 63
	s_mul_i32 s6, s0, 0x1000000
	s_lshl_b32 s7, s4, 19
	s_add_u32 s6, s6, s7
	s_lshl_b32 s7, s5, 7
	s_add_u32 s6, s6, s7
	s_mul_i32 s7, s0, 0x800000
	s_add_u32 s7, s7, 0x3400000
	s_lshl_b32 s5, s5, 17
	s_add_u32 s7, s7, s5
	s_lshl_b32 s4, s4, 7
	s_add_u32 s7, s7, s4
	s_movk_i32 s12, 0x4000
	s_mov_b32 s13, 0x8000
	s_branch .LitA_p1c
.LitA_p1k3:
	s_sub_u32 s3, s3, 0x1a00
	s_cmpk_ge_u32 s3, 0x1600
	s_cselect_b32 s7, 0x80000, 0
	s_cselect_b32 s5, 0x1600, 0
	s_cbranch_scc1 .LitA_p1up
	s_load_dwordx2 s[8:9], s[58:59], 0xb0
	s_branch .LitA_p1gu
.LitA_p1up:
	s_load_dwordx2 s[8:9], s[58:59], 0xb8
.LitA_p1gu:
	s_sub_u32 s3, s3, s5
	s_mul_i32 s4, s3, 0x1745e
	s_lshr_b32 s4, s4, 24
	s_mul_i32 s5, s4, 0xb0
	s_sub_u32 s5, s3, s5
	s_mul_i32 s6, s0, 0x2c00000
	s_mul_i32 s3, s4, 0x160000
	s_add_u32 s6, s6, s3
	s_lshl_b32 s3, s5, 7
	s_add_u32 s6, s6, s3
	s_mul_i32 s3, s0, 0x2c00000
	s_add_u32 s7, s7, s3
	s_add_u32 s7, s7, 0x4400000
	s_lshr_b32 s3, s5, 2
	s_lshl_b32 s3, s3, 20
	s_add_u32 s7, s7, s3
	s_and_b32 s3, s5, 3
	s_lshl_b32 s3, s3, 17
	s_add_u32 s7, s7, s3
	s_lshl_b32 s4, s4, 7
	s_add_u32 s7, s7, s4
	s_mov_b32 s12, 0xb000
	s_mov_b32 s13, 0x8000
.LitA_p1c:
	s_lshr_b32 s4, s12, 1
	s_lshr_b32 s5, s13, 3
	v_mad_u32_u24 v11, v5, s4, v6
	v_mad_u32_u24 v0, v7, s5, v8
	s_add_u32 s10, s56, s7
	s_addc_u32 s11, s57, 0
	s_waitcnt lgkmcnt(0)
	s_add_u32 s8, s8, s6
	s_addc_u32 s9, s9, 0
	global_load_dword v20, v11, s[8:9] nt
	s_add_u32 s8, s8, s12
	s_addc_u32 s9, s9, 0
	global_load_dword v21, v11, s[8:9] nt
	s_add_u32 s8, s8, s12
	s_addc_u32 s9, s9, 0
	global_load_dword v22, v11, s[8:9] nt
	s_add_u32 s8, s8, s12
	s_addc_u32 s9, s9, 0
	global_load_dword v23, v11, s[8:9] nt
	s_add_u32 s8, s8, s12
	s_addc_u32 s9, s9, 0
	global_load_dword v24, v11, s[8:9] nt
	s_add_u32 s8, s8, s12
	s_addc_u32 s9, s9, 0
	global_load_dword v25, v11, s[8:9] nt
	s_add_u32 s8, s8, s12
	s_addc_u32 s9, s9, 0
	global_load_dword v26, v11, s[8:9] nt
	s_add_u32 s8, s8, s12
	s_addc_u32 s9, s9, 0
	global_load_dword v27, v11, s[8:9] nt
	s_add_u32 s8, s8, s12
	s_addc_u32 s9, s9, 0
	global_load_dword v28, v11, s[8:9] nt
	s_add_u32 s8, s8, s12
	s_addc_u32 s9, s9, 0
	global_load_dword v29, v11, s[8:9] nt
	s_add_u32 s8, s8, s12
	s_addc_u32 s9, s9, 0
	global_load_dword v30, v11, s[8:9] nt
	s_add_u32 s8, s8, s12
	s_addc_u32 s9, s9, 0
	global_load_dword v31, v11, s[8:9] nt
	s_add_u32 s8, s8, s12
	s_addc_u32 s9, s9, 0
	global_load_dword v32, v11, s[8:9] nt
	s_add_u32 s8, s8, s12
	s_addc_u32 s9, s9, 0
	global_load_dword v33, v11, s[8:9] nt
	s_add_u32 s8, s8, s12
	s_addc_u32 s9, s9, 0
	global_load_dword v34, v11, s[8:9] nt
	s_add_u32 s8, s8, s12
	s_addc_u32 s9, s9, 0
	global_load_dword v35, v11, s[8:9] nt
	s_add_u32 s8, s8, s12
	s_addc_u32 s9, s9, 0
	global_load_dword v36, v11, s[8:9] nt
	s_add_u32 s8, s8, s12
	s_addc_u32 s9, s9, 0
	global_load_dword v37, v11, s[8:9] nt
	s_add_u32 s8, s8, s12
	s_addc_u32 s9, s9, 0
	global_load_dword v38, v11, s[8:9] nt
	s_add_u32 s8, s8, s12
	s_addc_u32 s9, s9, 0
	global_load_dword v39, v11, s[8:9] nt
	s_add_u32 s8, s8, s12
	s_addc_u32 s9, s9, 0
	global_load_dword v40, v11, s[8:9] nt
	s_add_u32 s8, s8, s12
	s_addc_u32 s9, s9, 0
	global_load_dword v41, v11, s[8:9] nt
	s_add_u32 s8, s8, s12
	s_addc_u32 s9, s9, 0
	global_load_dword v42, v11, s[8:9] nt
	s_add_u32 s8, s8, s12
	s_addc_u32 s9, s9, 0
	global_load_dword v43, v11, s[8:9] nt
	s_add_u32 s8, s8, s12
	s_addc_u32 s9, s9, 0
	global_load_dword v44, v11, s[8:9] nt
	s_add_u32 s8, s8, s12
	s_addc_u32 s9, s9, 0
	global_load_dword v45, v11, s[8:9] nt
	s_add_u32 s8, s8, s12
	s_addc_u32 s9, s9, 0
	global_load_dword v46, v11, s[8:9] nt
	s_add_u32 s8, s8, s12
	s_addc_u32 s9, s9, 0
	global_load_dword v47, v11, s[8:9] nt
	s_add_u32 s8, s8, s12
	s_addc_u32 s9, s9, 0
	global_load_dword v48, v11, s[8:9] nt
	s_add_u32 s8, s8, s12
	s_addc_u32 s9, s9, 0
	global_load_dword v49, v11, s[8:9] nt
	s_add_u32 s8, s8, s12
	s_addc_u32 s9, s9, 0
	global_load_dword v50, v11, s[8:9] nt
	s_add_u32 s8, s8, s12
	s_addc_u32 s9, s9, 0
	global_load_dword v51, v11, s[8:9] nt
	s_add_i32 s25, s25, s1
	s_cmp_ge_i32 s25, s39
	s_cbranch_scc1 .LitA_dr_p1
	s_movk_i32 s4, 0x5c00
	s_cmp_ge_u32 s25, s4
	s_cselect_b32 s0, 1, 0
	s_cselect_b32 s5, s4, 0
	s_sub_u32 s3, s25, s5
	s_cmpk_lt_u32 s3, 0x1000
	s_cbranch_scc1 .LitA_p2k0
	s_cmpk_lt_u32 s3, 0x1200
	s_cbranch_scc1 .LitA_p2k1
	s_cmpk_lt_u32 s3, 0x1a00
	s_cbranch_scc1 .LitA_p2k2
	s_cmpk_lt_u32 s3, 0x4600
	s_cbranch_scc1 .LitA_p2k3
	s_load_dwordx2 s[18:19], s[58:59], 0xc0
	s_sub_u32 s3, s3, 0x4600
	s_lshr_b32 s4, s3, 6
	s_and_b32 s5, s3, 63
	s_mul_i32 s6, s0, 0x2c00000
	s_lshl_b32 s7, s4, 19
	s_add_u32 s6, s6, s7
	s_lshl_b32 s7, s5, 7
	s_add_u32 s6, s6, s7
	s_mul_i32 s7, s0, 0x1600000
	s_add_u32 s7, s7, 0x9c00000
	s_mul_i32 s5, s5, 0x58000
	s_add_u32 s7, s7, s5
	s_lshl_b32 s4, s4, 7
	s_add_u32 s7, s7, s4
	s_movk_i32 s15, 0x4000
	s_mov_b32 s20, 0x16000
	s_branch .LitA_p2c
.LitA_p2k0:
	s_load_dwordx2 s[18:19], s[58:59], 0x40
	s_lshr_b32 s4, s3, 7
	s_and_b32 s5, s3, 127
	s_mul_i32 s6, s0, 0x2000000
	s_lshl_b32 s7, s4, 20
	s_add_u32 s6, s6, s7
	s_lshl_b32 s7, s5, 7
	s_add_u32 s6, s6, s7
	s_mul_i32 s7, s0, 0x1000000
	s_add_u32 s7, s7, 0x1000000
	s_lshl_b32 s5, s5, 17
	s_add_u32 s7, s7, s5
	s_lshl_b32 s4, s4, 7
	s_add_u32 s7, s7, s4
	s_mov_b32 s15, 0x8000
	s_mov_b32 s20, 0x8000
	s_branch .LitA_p2c
.LitA_p2k1:
	s_load_dwordx2 s[18:19], s[58:59], 0x88
	s_sub_u32 s3, s3, 0x1000
	s_lshr_b32 s4, s3, 5
	s_and_b32 s5, s3, 31
	s_mul_i32 s6, s0, 0x400000
	s_lshl_b32 s7, s4, 18
	s_add_u32 s6, s6, s7
	s_lshl_b32 s7, s5, 7
	s_add_u32 s6, s6, s7
	s_mul_i32 s7, s0, 0x200000
	s_add_u32 s7, s7, 0x3000000
	s_lshl_b32 s5, s5, 16
	s_add_u32 s7, s7, s5
	s_lshl_b32 s4, s4, 7
	s_add_u32 s7, s7, s4
	s_movk_i32 s15, 0x2000
	s_movk_i32 s20, 0x4000
	s_branch .LitA_p2c
.LitA_p2k2:
	s_load_dwordx2 s[18:19], s[58:59], 0xa0
	s_sub_u32 s3, s3, 0x1200
	s_lshr_b32 s4, s3, 6
	s_and_b32 s5, s3, 63
	s_mul_i32 s6, s0, 0x1000000
	s_lshl_b32 s7, s4, 19
	s_add_u32 s6, s6, s7
	s_lshl_b32 s7, s5, 7
	s_add_u32 s6, s6, s7
	s_mul_i32 s7, s0, 0x800000
	s_add_u32 s7, s7, 0x3400000
	s_lshl_b32 s5, s5, 17
	s_add_u32 s7, s7, s5
	s_lshl_b32 s4, s4, 7
	s_add_u32 s7, s7, s4
	s_movk_i32 s15, 0x4000
	s_mov_b32 s20, 0x8000
	s_branch .LitA_p2c
.LitA_p2k3:
	s_sub_u32 s3, s3, 0x1a00
	s_cmpk_ge_u32 s3, 0x1600
	s_cselect_b32 s7, 0x80000, 0
	s_cselect_b32 s5, 0x1600, 0
	s_cbranch_scc1 .LitA_p2up
	s_load_dwordx2 s[18:19], s[58:59], 0xb0
	s_branch .LitA_p2gu
.LitA_p2up:
	s_load_dwordx2 s[18:19], s[58:59], 0xb8
.LitA_p2gu:
	s_sub_u32 s3, s3, s5
	s_mul_i32 s4, s3, 0x1745e
	s_lshr_b32 s4, s4, 24
	s_mul_i32 s5, s4, 0xb0
	s_sub_u32 s5, s3, s5
	s_mul_i32 s6, s0, 0x2c00000
	s_mul_i32 s3, s4, 0x160000
	s_add_u32 s6, s6, s3
	s_lshl_b32 s3, s5, 7
	s_add_u32 s6, s6, s3
	s_mul_i32 s3, s0, 0x2c00000
	s_add_u32 s7, s7, s3
	s_add_u32 s7, s7, 0x4400000
	s_lshr_b32 s3, s5, 2
	s_lshl_b32 s3, s3, 20
	s_add_u32 s7, s7, s3
	s_and_b32 s3, s5, 3
	s_lshl_b32 s3, s3, 17
	s_add_u32 s7, s7, s3
	s_lshl_b32 s4, s4, 7
	s_add_u32 s7, s7, s4
	s_mov_b32 s15, 0xb000
	s_mov_b32 s20, 0x8000
.LitA_p2c:
	s_lshr_b32 s4, s15, 1
	s_lshr_b32 s5, s20, 3
	v_mad_u32_u24 v12, v5, s4, v6
	v_mad_u32_u24 v1, v7, s5, v8
	s_add_u32 s36, s56, s7
	s_addc_u32 s37, s57, 0
	s_waitcnt lgkmcnt(0)
	s_add_u32 s18, s18, s6
	s_addc_u32 s19, s19, 0
	global_load_dword v52, v12, s[18:19] nt
	s_add_u32 s18, s18, s15
	s_addc_u32 s19, s19, 0
	global_load_dword v53, v12, s[18:19] nt
	s_add_u32 s18, s18, s15
	s_addc_u32 s19, s19, 0
	global_load_dword v54, v12, s[18:19] nt
	s_add_u32 s18, s18, s15
	s_addc_u32 s19, s19, 0
	global_load_dword v55, v12, s[18:19] nt
	s_add_u32 s18, s18, s15
	s_addc_u32 s19, s19, 0
	global_load_dword v56, v12, s[18:19] nt
	s_add_u32 s18, s18, s15
	s_addc_u32 s19, s19, 0
	global_load_dword v57, v12, s[18:19] nt
	s_add_u32 s18, s18, s15
	s_addc_u32 s19, s19, 0
	global_load_dword v58, v12, s[18:19] nt
	s_add_u32 s18, s18, s15
	s_addc_u32 s19, s19, 0
	global_load_dword v59, v12, s[18:19] nt
	s_add_u32 s18, s18, s15
	s_addc_u32 s19, s19, 0
	global_load_dword v60, v12, s[18:19] nt
	s_add_u32 s18, s18, s15
	s_addc_u32 s19, s19, 0
	global_load_dword v61, v12, s[18:19] nt
	s_add_u32 s18, s18, s15
	s_addc_u32 s19, s19, 0
	global_load_dword v62, v12, s[18:19] nt
	s_add_u32 s18, s18, s15
	s_addc_u32 s19, s19, 0
	global_load_dword v63, v12, s[18:19] nt
	s_add_u32 s18, s18, s15
	s_addc_u32 s19, s19, 0
	global_load_dword v64, v12, s[18:19] nt
	s_add_u32 s18, s18, s15
	s_addc_u32 s19, s19, 0
	global_load_dword v65, v12, s[18:19] nt
	s_add_u32 s18, s18, s15
	s_addc_u32 s19, s19, 0
	global_load_dword v66, v12, s[18:19] nt
	s_add_u32 s18, s18, s15
	s_addc_u32 s19, s19, 0
	global_load_dword v67, v12, s[18:19] nt
	s_add_u32 s18, s18, s15
	s_addc_u32 s19, s19, 0
	global_load_dword v68, v12, s[18:19] nt
	s_add_u32 s18, s18, s15
	s_addc_u32 s19, s19, 0
	global_load_dword v69, v12, s[18:19] nt
	s_add_u32 s18, s18, s15
	s_addc_u32 s19, s19, 0
	global_load_dword v70, v12, s[18:19] nt
	s_add_u32 s18, s18, s15
	s_addc_u32 s19, s19, 0
	global_load_dword v71, v12, s[18:19] nt
	s_add_u32 s18, s18, s15
	s_addc_u32 s19, s19, 0
	global_load_dword v72, v12, s[18:19] nt
	s_add_u32 s18, s18, s15
	s_addc_u32 s19, s19, 0
	global_load_dword v73, v12, s[18:19] nt
	s_add_u32 s18, s18, s15
	s_addc_u32 s19, s19, 0
	global_load_dword v74, v12, s[18:19] nt
	s_add_u32 s18, s18, s15
	s_addc_u32 s19, s19, 0
	global_load_dword v75, v12, s[18:19] nt
	s_add_u32 s18, s18, s15
	s_addc_u32 s19, s19, 0
	global_load_dword v76, v12, s[18:19] nt
	s_add_u32 s18, s18, s15
	s_addc_u32 s19, s19, 0
	global_load_dword v77, v12, s[18:19] nt
	s_add_u32 s18, s18, s15
	s_addc_u32 s19, s19, 0
	global_load_dword v78, v12, s[18:19] nt
	s_add_u32 s18, s18, s15
	s_addc_u32 s19, s19, 0
	global_load_dword v79, v12, s[18:19] nt
	s_add_u32 s18, s18, s15
	s_addc_u32 s19, s19, 0
	global_load_dword v80, v12, s[18:19] nt
	s_add_u32 s18, s18, s15
	s_addc_u32 s19, s19, 0
	global_load_dword v81, v12, s[18:19] nt
	s_add_u32 s18, s18, s15
	s_addc_u32 s19, s19, 0
	global_load_dword v82, v12, s[18:19] nt
	s_add_u32 s18, s18, s15
	s_addc_u32 s19, s19, 0
	global_load_dword v83, v12, s[18:19] nt
	s_add_i32 s25, s25, s1
	s_cmp_ge_i32 s25, s39
	s_cbranch_scc1 .LitA_dr_p2
	s_movk_i32 s4, 0x5c00
	s_cmp_ge_u32 s25, s4
	s_cselect_b32 s0, 1, 0
	s_cselect_b32 s5, s4, 0
	s_sub_u32 s3, s25, s5
	s_cmpk_lt_u32 s3, 0x1000
	s_cbranch_scc1 .LitA_p3k0
	s_cmpk_lt_u32 s3, 0x1200
	s_cbranch_scc1 .LitA_p3k1
	s_cmpk_lt_u32 s3, 0x1a00
	s_cbranch_scc1 .LitA_p3k2
	s_cmpk_lt_u32 s3, 0x4600
	s_cbranch_scc1 .LitA_p3k3
	s_load_dwordx2 s[40:41], s[58:59], 0xc0
	s_sub_u32 s3, s3, 0x4600
	s_lshr_b32 s4, s3, 6
	s_and_b32 s5, s3, 63
	s_mul_i32 s6, s0, 0x2c00000
	s_lshl_b32 s7, s4, 19
	s_add_u32 s6, s6, s7
	s_lshl_b32 s7, s5, 7
	s_add_u32 s6, s6, s7
	s_mul_i32 s7, s0, 0x1600000
	s_add_u32 s7, s7, 0x9c00000
	s_mul_i32 s5, s5, 0x58000
	s_add_u32 s7, s7, s5
	s_lshl_b32 s4, s4, 7
	s_add_u32 s7, s7, s4
	s_movk_i32 s38, 0x4000
	s_mov_b32 s42, 0x16000
	s_branch .LitA_p3c
.LitA_p3k0:
	s_load_dwordx2 s[40:41], s[58:59], 0x40
	s_lshr_b32 s4, s3, 7
	s_and_b32 s5, s3, 127
	s_mul_i32 s6, s0, 0x2000000
	s_lshl_b32 s7, s4, 20
	s_add_u32 s6, s6, s7
	s_lshl_b32 s7, s5, 7
	s_add_u32 s6, s6, s7
	s_mul_i32 s7, s0, 0x1000000
	s_add_u32 s7, s7, 0x1000000
	s_lshl_b32 s5, s5, 17
	s_add_u32 s7, s7, s5
	s_lshl_b32 s4, s4, 7
	s_add_u32 s7, s7, s4
	s_mov_b32 s38, 0x8000
	s_mov_b32 s42, 0x8000
	s_branch .LitA_p3c
.LitA_p3k1:
	s_load_dwordx2 s[40:41], s[58:59], 0x88
	s_sub_u32 s3, s3, 0x1000
	s_lshr_b32 s4, s3, 5
	s_and_b32 s5, s3, 31
	s_mul_i32 s6, s0, 0x400000
	s_lshl_b32 s7, s4, 18
	s_add_u32 s6, s6, s7
	s_lshl_b32 s7, s5, 7
	s_add_u32 s6, s6, s7
	s_mul_i32 s7, s0, 0x200000
	s_add_u32 s7, s7, 0x3000000
	s_lshl_b32 s5, s5, 16
	s_add_u32 s7, s7, s5
	s_lshl_b32 s4, s4, 7
	s_add_u32 s7, s7, s4
	s_movk_i32 s38, 0x2000
	s_movk_i32 s42, 0x4000
	s_branch .LitA_p3c
.LitA_p3k2:
	s_load_dwordx2 s[40:41], s[58:59], 0xa0
	s_sub_u32 s3, s3, 0x1200
	s_lshr_b32 s4, s3, 6
	s_and_b32 s5, s3, 63
	s_mul_i32 s6, s0, 0x1000000
	s_lshl_b32 s7, s4, 19
	s_add_u32 s6, s6, s7
	s_lshl_b32 s7, s5, 7
	s_add_u32 s6, s6, s7
	s_mul_i32 s7, s0, 0x800000
	s_add_u32 s7, s7, 0x3400000
	s_lshl_b32 s5, s5, 17
	s_add_u32 s7, s7, s5
	s_lshl_b32 s4, s4, 7
	s_add_u32 s7, s7, s4
	s_movk_i32 s38, 0x4000
	s_mov_b32 s42, 0x8000
	s_branch .LitA_p3c
.LitA_p3k3:
	s_sub_u32 s3, s3, 0x1a00
	s_cmpk_ge_u32 s3, 0x1600
	s_cselect_b32 s7, 0x80000, 0
	s_cselect_b32 s5, 0x1600, 0
	s_cbranch_scc1 .LitA_p3up
	s_load_dwordx2 s[40:41], s[58:59], 0xb0
	s_branch .LitA_p3gu
.LitA_p3up:
	s_load_dwordx2 s[40:41], s[58:59], 0xb8
.LitA_p3gu:
	s_sub_u32 s3, s3, s5
	s_mul_i32 s4, s3, 0x1745e
	s_lshr_b32 s4, s4, 24
	s_mul_i32 s5, s4, 0xb0
	s_sub_u32 s5, s3, s5
	s_mul_i32 s6, s0, 0x2c00000
	s_mul_i32 s3, s4, 0x160000
	s_add_u32 s6, s6, s3
	s_lshl_b32 s3, s5, 7
	s_add_u32 s6, s6, s3
	s_mul_i32 s3, s0, 0x2c00000
	s_add_u32 s7, s7, s3
	s_add_u32 s7, s7, 0x4400000
	s_lshr_b32 s3, s5, 2
	s_lshl_b32 s3, s3, 20
	s_add_u32 s7, s7, s3
	s_and_b32 s3, s5, 3
	s_lshl_b32 s3, s3, 17
	s_add_u32 s7, s7, s3
	s_lshl_b32 s4, s4, 7
	s_add_u32 s7, s7, s4
	s_mov_b32 s38, 0xb000
	s_mov_b32 s42, 0x8000
.LitA_p3c:
	s_lshr_b32 s4, s38, 1
	s_lshr_b32 s5, s42, 3
	v_mad_u32_u24 v13, v5, s4, v6
	v_mad_u32_u24 v2, v7, s5, v8
	s_add_u32 s44, s56, s7
	s_addc_u32 s45, s57, 0
	s_waitcnt lgkmcnt(0)
	s_add_u32 s40, s40, s6
	s_addc_u32 s41, s41, 0
	global_load_dword v84, v13, s[40:41] nt
	s_add_u32 s40, s40, s38
	s_addc_u32 s41, s41, 0
	global_load_dword v85, v13, s[40:41] nt
	s_add_u32 s40, s40, s38
	s_addc_u32 s41, s41, 0
	global_load_dword v86, v13, s[40:41] nt
	s_add_u32 s40, s40, s38
	s_addc_u32 s41, s41, 0
	global_load_dword v87, v13, s[40:41] nt
	s_add_u32 s40, s40, s38
	s_addc_u32 s41, s41, 0
	global_load_dword v88, v13, s[40:41] nt
	s_add_u32 s40, s40, s38
	s_addc_u32 s41, s41, 0
	global_load_dword v89, v13, s[40:41] nt
	s_add_u32 s40, s40, s38
	s_addc_u32 s41, s41, 0
	global_load_dword v90, v13, s[40:41] nt
	s_add_u32 s40, s40, s38
	s_addc_u32 s41, s41, 0
	global_load_dword v91, v13, s[40:41] nt
	s_add_u32 s40, s40, s38
	s_addc_u32 s41, s41, 0
	global_load_dword v92, v13, s[40:41] nt
	s_add_u32 s40, s40, s38
	s_addc_u32 s41, s41, 0
	global_load_dword v93, v13, s[40:41] nt
	s_add_u32 s40, s40, s38
	s_addc_u32 s41, s41, 0
	global_load_dword v94, v13, s[40:41] nt
	s_add_u32 s40, s40, s38
	s_addc_u32 s41, s41, 0
	global_load_dword v95, v13, s[40:41] nt
	s_add_u32 s40, s40, s38
	s_addc_u32 s41, s41, 0
	global_load_dword v96, v13, s[40:41] nt
	s_add_u32 s40, s40, s38
	s_addc_u32 s41, s41, 0
	global_load_dword v97, v13, s[40:41] nt
	s_add_u32 s40, s40, s38
	s_addc_u32 s41, s41, 0
	global_load_dword v98, v13, s[40:41] nt
	s_add_u32 s40, s40, s38
	s_addc_u32 s41, s41, 0
	global_load_dword v99, v13, s[40:41] nt
	s_add_u32 s40, s40, s38
	s_addc_u32 s41, s41, 0
	global_load_dword v100, v13, s[40:41] nt
	s_add_u32 s40, s40, s38
	s_addc_u32 s41, s41, 0
	global_load_dword v101, v13, s[40:41] nt
	s_add_u32 s40, s40, s38
	s_addc_u32 s41, s41, 0
	global_load_dword v102, v13, s[40:41] nt
	s_add_u32 s40, s40, s38
	s_addc_u32 s41, s41, 0
	global_load_dword v103, v13, s[40:41] nt
	s_add_u32 s40, s40, s38
	s_addc_u32 s41, s41, 0
	global_load_dword v104, v13, s[40:41] nt
	s_add_u32 s40, s40, s38
	s_addc_u32 s41, s41, 0
	global_load_dword v105, v13, s[40:41] nt
	s_add_u32 s40, s40, s38
	s_addc_u32 s41, s41, 0
	global_load_dword v106, v13, s[40:41] nt
	s_add_u32 s40, s40, s38
	s_addc_u32 s41, s41, 0
	global_load_dword v107, v13, s[40:41] nt
	s_add_u32 s40, s40, s38
	s_addc_u32 s41, s41, 0
	global_load_dword v108, v13, s[40:41] nt
	s_add_u32 s40, s40, s38
	s_addc_u32 s41, s41, 0
	global_load_dword v109, v13, s[40:41] nt
	s_add_u32 s40, s40, s38
	s_addc_u32 s41, s41, 0
	global_load_dword v110, v13, s[40:41] nt
	s_add_u32 s40, s40, s38
	s_addc_u32 s41, s41, 0
	global_load_dword v111, v13, s[40:41] nt
	s_add_u32 s40, s40, s38
	s_addc_u32 s41, s41, 0
	global_load_dword v112, v13, s[40:41] nt
	s_add_u32 s40, s40, s38
	s_addc_u32 s41, s41, 0
	global_load_dword v113, v13, s[40:41] nt
	s_add_u32 s40, s40, s38
	s_addc_u32 s41, s41, 0
	global_load_dword v114, v13, s[40:41] nt
	s_add_u32 s40, s40, s38
	s_addc_u32 s41, s41, 0
	global_load_dword v115, v13, s[40:41] nt
	s_add_i32 s25, s25, s1
.LitA_loop:
	s_waitcnt vmcnt(63)
	ds_write_b32 v9, v20
	ds_write_b32 v9, v21 offset:264
	ds_write_b32 v9, v22 offset:528
	ds_write_b32 v9, v23 offset:792
	ds_write_b32 v9, v24 offset:1056
	ds_write_b32 v9, v25 offset:1320
	ds_write_b32 v9, v26 offset:1584
	ds_write_b32 v9, v27 offset:1848
	ds_write_b32 v9, v28 offset:2112
	ds_write_b32 v9, v29 offset:2376
	ds_write_b32 v9, v30 offset:2640
	ds_write_b32 v9, v31 offset:2904
	ds_write_b32 v9, v32 offset:3168
	ds_write_b32 v9, v33 offset:3432
	ds_write_b32 v9, v34 offset:3696
	ds_write_b32 v9, v35 offset:3960
	ds_write_b32 v9, v36 offset:4224
	ds_write_b32 v9, v37 offset:4488
	ds_write_b32 v9, v38 offset:4752
	ds_write_b32 v9, v39 offset:5016
	ds_write_b32 v9, v40 offset:5280
	ds_write_b32 v9, v41 offset:5544
	ds_write_b32 v9, v42 offset:5808
	ds_write_b32 v9, v43 offset:6072
	ds_write_b32 v9, v44 offset:6336
	ds_write_b32 v9, v45 offset:6600
	ds_write_b32 v9, v46 offset:6864
	ds_write_b32 v9, v47 offset:7128
	ds_write_b32 v9, v48 offset:7392
	ds_write_b32 v9, v49 offset:7656
	ds_write_b32 v9, v50 offset:7920
	ds_write_b32 v9, v51 offset:8184
	ds_read2_b32 v[116:117], v10 offset0:0 offset1:33
	ds_read2_b32 v[118:119], v10 offset0:66 offset1:99
	ds_read2_b32 v[120:121], v10 offset0:132 offset1:165
	ds_read2_b32 v[122:123], v10 offset0:198 offset1:231
	ds_read2_b32 v[124:125], v10 offset0:8 offset1:41
	ds_read2_b32 v[126:127], v10 offset0:74 offset1:107
	ds_read2_b32 v[128:129], v10 offset0:140 offset1:173
	ds_read2_b32 v[130:131], v10 offset0:206 offset1:239
	ds_read2_b32 v[132:133], v10 offset0:16 offset1:49
	ds_read2_b32 v[134:135], v10 offset0:82 offset1:115
	ds_read2_b32 v[136:137], v10 offset0:148 offset1:181
	ds_read2_b32 v[138:139], v10 offset0:214 offset1:247
	ds_read2_b32 v[140:141], v10 offset0:24 offset1:57
	ds_read2_b32 v[142:143], v10 offset0:90 offset1:123
	ds_read2_b32 v[144:145], v10 offset0:156 offset1:189
	ds_read2_b32 v[146:147], v10 offset0:222 offset1:255
	s_waitcnt lgkmcnt(12)
	v_cvt_pk_bf16_f32 v170, v116, v117
	v_cvt_pk_bf16_f32 v171, v118, v119
	v_cvt_pk_bf16_f32 v172, v120, v121
	v_cvt_pk_bf16_f32 v173, v122, v123
	global_store_dwordx4 v0, v[170:173], s[10:11]
	s_add_u32 s10, s10, s13
	s_addc_u32 s11, s11, 0
	s_waitcnt lgkmcnt(8)
	v_cvt_pk_bf16_f32 v174, v124, v125
	v_cvt_pk_bf16_f32 v175, v126, v127
	v_cvt_pk_bf16_f32 v176, v128, v129
	v_cvt_pk_bf16_f32 v177, v130, v131
	global_store_dwordx4 v0, v[174:177], s[10:11]
	s_add_u32 s10, s10, s13
	s_addc_u32 s11, s11, 0
	s_waitcnt lgkmcnt(4)
	v_cvt_pk_bf16_f32 v178, v132, v133
	v_cvt_pk_bf16_f32 v179, v134, v135
	v_cvt_pk_bf16_f32 v180, v136, v137
	v_cvt_pk_bf16_f32 v181, v138, v139
	global_store_dwordx4 v0, v[178:181], s[10:11]
	s_add_u32 s10, s10, s13
	s_addc_u32 s11, s11, 0
	s_waitcnt lgkmcnt(0)
	v_cvt_pk_bf16_f32 v182, v140, v141
	v_cvt_pk_bf16_f32 v183, v142, v143
	v_cvt_pk_bf16_f32 v184, v144, v145
	v_cvt_pk_bf16_f32 v185, v146, v147
	global_store_dwordx4 v0, v[182:185], s[10:11]
	s_cmp_ge_i32 s25, s39
	s_cbranch_scc1 .LitA_dr_l0
	s_movk_i32 s4, 0x5c00
	s_cmp_ge_u32 s25, s4
	s_cselect_b32 s0, 1, 0
	s_cselect_b32 s5, s4, 0
	s_sub_u32 s3, s25, s5
	s_cmpk_lt_u32 s3, 0x1000
	s_cbranch_scc1 .LitA_p4k0
	s_cmpk_lt_u32 s3, 0x1200
	s_cbranch_scc1 .LitA_p4k1
	s_cmpk_lt_u32 s3, 0x1a00
	s_cbranch_scc1 .LitA_p4k2
	s_cmpk_lt_u32 s3, 0x4600
	s_cbranch_scc1 .LitA_p4k3
	s_load_dwordx2 s[8:9], s[58:59], 0xc0
	s_sub_u32 s3, s3, 0x4600
	s_lshr_b32 s4, s3, 6
	s_and_b32 s5, s3, 63
	s_mul_i32 s6, s0, 0x2c00000
	s_lshl_b32 s7, s4, 19
	s_add_u32 s6, s6, s7
	s_lshl_b32 s7, s5, 7
	s_add_u32 s6, s6, s7
	s_mul_i32 s7, s0, 0x1600000
	s_add_u32 s7, s7, 0x9c00000
	s_mul_i32 s5, s5, 0x58000
	s_add_u32 s7, s7, s5
	s_lshl_b32 s4, s4, 7
	s_add_u32 s7, s7, s4
	s_movk_i32 s12, 0x4000
	s_mov_b32 s13, 0x16000
	s_branch .LitA_p4c

.LitA_p4c:
	s_lshr_b32 s4, s12, 1
	s_lshr_b32 s5, s13, 3
	v_mad_u32_u24 v11, v5, s4, v6
	v_mad_u32_u24 v0, v7, s5, v8
	s_add_u32 s10, s56, s7
	s_addc_u32 s11, s57, 0
	s_waitcnt lgkmcnt(0)
	s_add_u32 s8, s8, s6
	s_addc_u32 s9, s9, 0
	global_load_dword v20, v11, s[8:9] nt
	s_add_u32 s8, s8, s12
	s_addc_u32 s9, s9, 0
	global_load_dword v21, v11, s[8:9] nt
	s_add_u32 s8, s8, s12
	s_addc_u32 s9, s9, 0
	global_load_dword v22, v11, s[8:9] nt
	s_add_u32 s8, s8, s12
	s_addc_u32 s9, s9, 0
	global_load_dword v23, v11, s[8:9] nt
	s_add_u32 s8, s8, s12
	s_addc_u32 s9, s9, 0
	global_load_dword v24, v11, s[8:9] nt
	s_add_u32 s8, s8, s12
	s_addc_u32 s9, s9, 0
	global_load_dword v25, v11, s[8:9] nt
	s_add_u32 s8, s8, s12
	s_addc_u32 s9, s9, 0
	global_load_dword v26, v11, s[8:9] nt
	s_add_u32 s8, s8, s12
	s_addc_u32 s9, s9, 0
	global_load_dword v27, v11, s[8:9] nt
	s_add_u32 s8, s8, s12
	s_addc_u32 s9, s9, 0
	global_load_dword v28, v11, s[8:9] nt
	s_add_u32 s8, s8, s12
	s_addc_u32 s9, s9, 0
	global_load_dword v29, v11, s[8:9] nt
	s_add_u32 s8, s8, s12
	s_addc_u32 s9, s9, 0
	global_load_dword v30, v11, s[8:9] nt
	s_add_u32 s8, s8, s12
	s_addc_u32 s9, s9, 0
	global_load_dword v31, v11, s[8:9] nt
	s_add_u32 s8, s8, s12
	s_addc_u32 s9, s9, 0
	global_load_dword v32, v11, s[8:9] nt
	s_add_u32 s8, s8, s12
	s_addc_u32 s9, s9, 0
	global_load_dword v33, v11, s[8:9] nt
	s_add_u32 s8, s8, s12
	s_addc_u32 s9, s9, 0
	global_load_dword v34, v11, s[8:9] nt
	s_add_u32 s8, s8, s12
	s_addc_u32 s9, s9, 0
	global_load_dword v35, v11, s[8:9] nt
	s_add_u32 s8, s8, s12
	s_addc_u32 s9, s9, 0
	global_load_dword v36, v11, s[8:9] nt
	s_add_u32 s8, s8, s12
	s_addc_u32 s9, s9, 0
	global_load_dword v37, v11, s[8:9] nt
	s_add_u32 s8, s8, s12
	s_addc_u32 s9, s9, 0
	global_load_dword v38, v11, s[8:9] nt
	s_add_u32 s8, s8, s12
	s_addc_u32 s9, s9, 0
	global_load_dword v39, v11, s[8:9] nt
	s_add_u32 s8, s8, s12
	s_addc_u32 s9, s9, 0
	global_load_dword v40, v11, s[8:9] nt
	s_add_u32 s8, s8, s12
	s_addc_u32 s9, s9, 0
	global_load_dword v41, v11, s[8:9] nt
	s_add_u32 s8, s8, s12
	s_addc_u32 s9, s9, 0
	global_load_dword v42, v11, s[8:9] nt
	s_add_u32 s8, s8, s12
	s_addc_u32 s9, s9, 0
	global_load_dword v43, v11, s[8:9] nt
	s_add_u32 s8, s8, s12
	s_addc_u32 s9, s9, 0
	global_load_dword v44, v11, s[8:9] nt
	s_add_u32 s8, s8, s12
	s_addc_u32 s9, s9, 0
	global_load_dword v45, v11, s[8:9] nt
	s_add_u32 s8, s8, s12
	s_addc_u32 s9, s9, 0
	global_load_dword v46, v11, s[8:9] nt
	s_add_u32 s8, s8, s12
	s_addc_u32 s9, s9, 0
	global_load_dword v47, v11, s[8:9] nt
	s_add_u32 s8, s8, s12
	s_addc_u32 s9, s9, 0
	global_load_dword v48, v11, s[8:9] nt
	s_add_u32 s8, s8, s12
	s_addc_u32 s9, s9, 0
	global_load_dword v49, v11, s[8:9] nt
	s_add_u32 s8, s8, s12
	s_addc_u32 s9, s9, 0
	global_load_dword v50, v11, s[8:9] nt
	s_add_u32 s8, s8, s12
	s_addc_u32 s9, s9, 0
	global_load_dword v51, v11, s[8:9] nt
	s_add_i32 s25, s25, s1
	s_waitcnt vmcnt(63)
	ds_write_b32 v9, v52
	ds_write_b32 v9, v53 offset:264
	ds_write_b32 v9, v54 offset:528
	ds_write_b32 v9, v55 offset:792
	ds_write_b32 v9, v56 offset:1056
	ds_write_b32 v9, v57 offset:1320
	ds_write_b32 v9, v58 offset:1584
	ds_write_b32 v9, v59 offset:1848
	ds_write_b32 v9, v60 offset:2112
	ds_write_b32 v9, v61 offset:2376
	ds_write_b32 v9, v62 offset:2640
	ds_write_b32 v9, v63 offset:2904
	ds_write_b32 v9, v64 offset:3168
	ds_write_b32 v9, v65 offset:3432
	ds_write_b32 v9, v66 offset:3696
	ds_write_b32 v9, v67 offset:3960
	ds_write_b32 v9, v68 offset:4224
	ds_write_b32 v9, v69 offset:4488
	ds_write_b32 v9, v70 offset:4752
	ds_write_b32 v9, v71 offset:5016
	ds_write_b32 v9, v72 offset:5280
	ds_write_b32 v9, v73 offset:5544
	ds_write_b32 v9, v74 offset:5808
	ds_write_b32 v9, v75 offset:6072
	ds_write_b32 v9, v76 offset:6336
	ds_write_b32 v9, v77 offset:6600
	ds_write_b32 v9, v78 offset:6864
	ds_write_b32 v9, v79 offset:7128
	ds_write_b32 v9, v80 offset:7392
	ds_write_b32 v9, v81 offset:7656
	ds_write_b32 v9, v82 offset:7920
	ds_write_b32 v9, v83 offset:8184
	ds_read2_b32 v[116:117], v10 offset0:0 offset1:33
	ds_read2_b32 v[118:119], v10 offset0:66 offset1:99
	ds_read2_b32 v[120:121], v10 offset0:132 offset1:165
	ds_read2_b32 v[122:123], v10 offset0:198 offset1:231
	ds_read2_b32 v[124:125], v10 offset0:8 offset1:41
	ds_read2_b32 v[126:127], v10 offset0:74 offset1:107
	ds_read2_b32 v[128:129], v10 offset0:140 offset1:173
	ds_read2_b32 v[130:131], v10 offset0:206 offset1:239
	ds_read2_b32 v[132:133], v10 offset0:16 offset1:49
	ds_read2_b32 v[134:135], v10 offset0:82 offset1:115
	ds_read2_b32 v[136:137], v10 offset0:148 offset1:181
	ds_read2_b32 v[138:139], v10 offset0:214 offset1:247
	ds_read2_b32 v[140:141], v10 offset0:24 offset1:57
	ds_read2_b32 v[142:143], v10 offset0:90 offset1:123
	ds_read2_b32 v[144:145], v10 offset0:156 offset1:189
	ds_read2_b32 v[146:147], v10 offset0:222 offset1:255
	s_waitcnt lgkmcnt(12)
	v_cvt_pk_bf16_f32 v170, v116, v117
	v_cvt_pk_bf16_f32 v171, v118, v119
	v_cvt_pk_bf16_f32 v172, v120, v121
	v_cvt_pk_bf16_f32 v173, v122, v123
	global_store_dwordx4 v1, v[170:173], s[36:37]
	s_add_u32 s36, s36, s20
	s_addc_u32 s37, s37, 0
	s_waitcnt lgkmcnt(8)
	v_cvt_pk_bf16_f32 v174, v124, v125
	v_cvt_pk_bf16_f32 v175, v126, v127
	v_cvt_pk_bf16_f32 v176, v128, v129
	v_cvt_pk_bf16_f32 v177, v130, v131
	global_store_dwordx4 v1, v[174:177], s[36:37]
	s_add_u32 s36, s36, s20
	s_addc_u32 s37, s37, 0
	s_waitcnt lgkmcnt(4)
	v_cvt_pk_bf16_f32 v178, v132, v133
	v_cvt_pk_bf16_f32 v179, v134, v135
	v_cvt_pk_bf16_f32 v180, v136, v137
	v_cvt_pk_bf16_f32 v181, v138, v139
	global_store_dwordx4 v1, v[178:181], s[36:37]
	s_add_u32 s36, s36, s20
	s_addc_u32 s37, s37, 0
	s_waitcnt lgkmcnt(0)
	v_cvt_pk_bf16_f32 v182, v140, v141
	v_cvt_pk_bf16_f32 v183, v142, v143
	v_cvt_pk_bf16_f32 v184, v144, v145
	v_cvt_pk_bf16_f32 v185, v146, v147
	global_store_dwordx4 v1, v[182:185], s[36:37]
	s_cmp_ge_i32 s25, s39
	s_cbranch_scc1 .LitA_dr_l1
	s_movk_i32 s4, 0x5c00
	s_cmp_ge_u32 s25, s4
	s_cselect_b32 s0, 1, 0
	s_cselect_b32 s5, s4, 0
	s_sub_u32 s3, s25, s5
	s_cmpk_lt_u32 s3, 0x1000
	s_cbranch_scc1 .LitA_p5k0
	s_cmpk_lt_u32 s3, 0x1200
	s_cbranch_scc1 .LitA_p5k1
	s_cmpk_lt_u32 s3, 0x1a00
	s_cbranch_scc1 .LitA_p5k2
	s_cmpk_lt_u32 s3, 0x4600
	s_cbranch_scc1 .LitA_p5k3
	s_load_dwordx2 s[18:19], s[58:59], 0xc0
	s_sub_u32 s3, s3, 0x4600
	s_lshr_b32 s4, s3, 6
	s_and_b32 s5, s3, 63
	s_mul_i32 s6, s0, 0x2c00000
	s_lshl_b32 s7, s4, 19
	s_add_u32 s6, s6, s7
	s_lshl_b32 s7, s5, 7
	s_add_u32 s6, s6, s7
	s_mul_i32 s7, s0, 0x1600000
	s_add_u32 s7, s7, 0x9c00000
	s_mul_i32 s5, s5, 0x58000
	s_add_u32 s7, s7, s5
	s_lshl_b32 s4, s4, 7
	s_add_u32 s7, s7, s4
	s_movk_i32 s15, 0x4000
	s_mov_b32 s20, 0x16000
	s_branch .LitA_p5c

.LitA_p5c:
	s_lshr_b32 s4, s15, 1
	s_lshr_b32 s5, s20, 3
	v_mad_u32_u24 v12, v5, s4, v6
	v_mad_u32_u24 v1, v7, s5, v8
	s_add_u32 s36, s56, s7
	s_addc_u32 s37, s57, 0
	s_waitcnt lgkmcnt(0)
	s_add_u32 s18, s18, s6
	s_addc_u32 s19, s19, 0
	global_load_dword v52, v12, s[18:19] nt
	s_add_u32 s18, s18, s15
	s_addc_u32 s19, s19, 0
	global_load_dword v53, v12, s[18:19] nt
	s_add_u32 s18, s18, s15
	s_addc_u32 s19, s19, 0
	global_load_dword v54, v12, s[18:19] nt
	s_add_u32 s18, s18, s15
	s_addc_u32 s19, s19, 0
	global_load_dword v55, v12, s[18:19] nt
	s_add_u32 s18, s18, s15
	s_addc_u32 s19, s19, 0
	global_load_dword v56, v12, s[18:19] nt
	s_add_u32 s18, s18, s15
	s_addc_u32 s19, s19, 0
	global_load_dword v57, v12, s[18:19] nt
	s_add_u32 s18, s18, s15
	s_addc_u32 s19, s19, 0
	global_load_dword v58, v12, s[18:19] nt
	s_add_u32 s18, s18, s15
	s_addc_u32 s19, s19, 0
	global_load_dword v59, v12, s[18:19] nt
	s_add_u32 s18, s18, s15
	s_addc_u32 s19, s19, 0
	global_load_dword v60, v12, s[18:19] nt
	s_add_u32 s18, s18, s15
	s_addc_u32 s19, s19, 0
	global_load_dword v61, v12, s[18:19] nt
	s_add_u32 s18, s18, s15
	s_addc_u32 s19, s19, 0
	global_load_dword v62, v12, s[18:19] nt
	s_add_u32 s18, s18, s15
	s_addc_u32 s19, s19, 0
	global_load_dword v63, v12, s[18:19] nt
	s_add_u32 s18, s18, s15
	s_addc_u32 s19, s19, 0
	global_load_dword v64, v12, s[18:19] nt
	s_add_u32 s18, s18, s15
	s_addc_u32 s19, s19, 0
	global_load_dword v65, v12, s[18:19] nt
	s_add_u32 s18, s18, s15
	s_addc_u32 s19, s19, 0
	global_load_dword v66, v12, s[18:19] nt
	s_add_u32 s18, s18, s15
	s_addc_u32 s19, s19, 0
	global_load_dword v67, v12, s[18:19] nt
	s_add_u32 s18, s18, s15
	s_addc_u32 s19, s19, 0
	global_load_dword v68, v12, s[18:19] nt
	s_add_u32 s18, s18, s15
	s_addc_u32 s19, s19, 0
	global_load_dword v69, v12, s[18:19] nt
	s_add_u32 s18, s18, s15
	s_addc_u32 s19, s19, 0
	global_load_dword v70, v12, s[18:19] nt
	s_add_u32 s18, s18, s15
	s_addc_u32 s19, s19, 0
	global_load_dword v71, v12, s[18:19] nt
	s_add_u32 s18, s18, s15
	s_addc_u32 s19, s19, 0
	global_load_dword v72, v12, s[18:19] nt
	s_add_u32 s18, s18, s15
	s_addc_u32 s19, s19, 0
	global_load_dword v73, v12, s[18:19] nt
	s_add_u32 s18, s18, s15
	s_addc_u32 s19, s19, 0
	global_load_dword v74, v12, s[18:19] nt
	s_add_u32 s18, s18, s15
	s_addc_u32 s19, s19, 0
	global_load_dword v75, v12, s[18:19] nt
	s_add_u32 s18, s18, s15
	s_addc_u32 s19, s19, 0
	global_load_dword v76, v12, s[18:19] nt
	s_add_u32 s18, s18, s15
	s_addc_u32 s19, s19, 0
	global_load_dword v77, v12, s[18:19] nt
	s_add_u32 s18, s18, s15
	s_addc_u32 s19, s19, 0
	global_load_dword v78, v12, s[18:19] nt
	s_add_u32 s18, s18, s15
	s_addc_u32 s19, s19, 0
	global_load_dword v79, v12, s[18:19] nt
	s_add_u32 s18, s18, s15
	s_addc_u32 s19, s19, 0
	global_load_dword v80, v12, s[18:19] nt
	s_add_u32 s18, s18, s15
	s_addc_u32 s19, s19, 0
	global_load_dword v81, v12, s[18:19] nt
	s_add_u32 s18, s18, s15
	s_addc_u32 s19, s19, 0
	global_load_dword v82, v12, s[18:19] nt
	s_add_u32 s18, s18, s15
	s_addc_u32 s19, s19, 0
	global_load_dword v83, v12, s[18:19] nt
	s_add_i32 s25, s25, s1
	s_waitcnt vmcnt(63)
	ds_write_b32 v9, v84
	ds_write_b32 v9, v85 offset:264
	ds_write_b32 v9, v86 offset:528
	ds_write_b32 v9, v87 offset:792
	ds_write_b32 v9, v88 offset:1056
	ds_write_b32 v9, v89 offset:1320
	ds_write_b32 v9, v90 offset:1584
	ds_write_b32 v9, v91 offset:1848
	ds_write_b32 v9, v92 offset:2112
	ds_write_b32 v9, v93 offset:2376
	ds_write_b32 v9, v94 offset:2640
	ds_write_b32 v9, v95 offset:2904
	ds_write_b32 v9, v96 offset:3168
	ds_write_b32 v9, v97 offset:3432
	ds_write_b32 v9, v98 offset:3696
	ds_write_b32 v9, v99 offset:3960
	ds_write_b32 v9, v100 offset:4224
	ds_write_b32 v9, v101 offset:4488
	ds_write_b32 v9, v102 offset:4752
	ds_write_b32 v9, v103 offset:5016
	ds_write_b32 v9, v104 offset:5280
	ds_write_b32 v9, v105 offset:5544
	ds_write_b32 v9, v106 offset:5808
	ds_write_b32 v9, v107 offset:6072
	ds_write_b32 v9, v108 offset:6336
	ds_write_b32 v9, v109 offset:6600
	ds_write_b32 v9, v110 offset:6864
	ds_write_b32 v9, v111 offset:7128
	ds_write_b32 v9, v112 offset:7392
	ds_write_b32 v9, v113 offset:7656
	ds_write_b32 v9, v114 offset:7920
	ds_write_b32 v9, v115 offset:8184
	ds_read2_b32 v[116:117], v10 offset0:0 offset1:33
	ds_read2_b32 v[118:119], v10 offset0:66 offset1:99
	ds_read2_b32 v[120:121], v10 offset0:132 offset1:165
	ds_read2_b32 v[122:123], v10 offset0:198 offset1:231
	ds_read2_b32 v[124:125], v10 offset0:8 offset1:41
	ds_read2_b32 v[126:127], v10 offset0:74 offset1:107
	ds_read2_b32 v[128:129], v10 offset0:140 offset1:173
	ds_read2_b32 v[130:131], v10 offset0:206 offset1:239
	ds_read2_b32 v[132:133], v10 offset0:16 offset1:49
	ds_read2_b32 v[134:135], v10 offset0:82 offset1:115
	ds_read2_b32 v[136:137], v10 offset0:148 offset1:181
	ds_read2_b32 v[138:139], v10 offset0:214 offset1:247
	ds_read2_b32 v[140:141], v10 offset0:24 offset1:57
	ds_read2_b32 v[142:143], v10 offset0:90 offset1:123
	ds_read2_b32 v[144:145], v10 offset0:156 offset1:189
	ds_read2_b32 v[146:147], v10 offset0:222 offset1:255
	s_waitcnt lgkmcnt(12)
	v_cvt_pk_bf16_f32 v170, v116, v117
	v_cvt_pk_bf16_f32 v171, v118, v119
	v_cvt_pk_bf16_f32 v172, v120, v121
	v_cvt_pk_bf16_f32 v173, v122, v123
	global_store_dwordx4 v2, v[170:173], s[44:45]
	s_add_u32 s44, s44, s42
	s_addc_u32 s45, s45, 0
	s_waitcnt lgkmcnt(8)
	v_cvt_pk_bf16_f32 v174, v124, v125
	v_cvt_pk_bf16_f32 v175, v126, v127
	v_cvt_pk_bf16_f32 v176, v128, v129
	v_cvt_pk_bf16_f32 v177, v130, v131
	global_store_dwordx4 v2, v[174:177], s[44:45]
	s_add_u32 s44, s44, s42
	s_addc_u32 s45, s45, 0
	s_waitcnt lgkmcnt(4)
	v_cvt_pk_bf16_f32 v178, v132, v133
	v_cvt_pk_bf16_f32 v179, v134, v135
	v_cvt_pk_bf16_f32 v180, v136, v137
	v_cvt_pk_bf16_f32 v181, v138, v139
	global_store_dwordx4 v2, v[178:181], s[44:45]
	s_add_u32 s44, s44, s42
	s_addc_u32 s45, s45, 0
	s_waitcnt lgkmcnt(0)
	v_cvt_pk_bf16_f32 v182, v140, v141
	v_cvt_pk_bf16_f32 v183, v142, v143
	v_cvt_pk_bf16_f32 v184, v144, v145
	v_cvt_pk_bf16_f32 v185, v146, v147
	global_store_dwordx4 v2, v[182:185], s[44:45]
	s_cmp_ge_i32 s25, s39
	s_cbranch_scc1 .LitA_dr_l2
	s_movk_i32 s4, 0x5c00
	s_cmp_ge_u32 s25, s4
	s_cselect_b32 s0, 1, 0
	s_cselect_b32 s5, s4, 0
	s_sub_u32 s3, s25, s5
	s_cmpk_lt_u32 s3, 0x1000
	s_cbranch_scc1 .LitA_p6k0
	s_cmpk_lt_u32 s3, 0x1200
	s_cbranch_scc1 .LitA_p6k1
	s_cmpk_lt_u32 s3, 0x1a00
	s_cbranch_scc1 .LitA_p6k2
	s_cmpk_lt_u32 s3, 0x4600
	s_cbranch_scc1 .LitA_p6k3
	s_load_dwordx2 s[40:41], s[58:59], 0xc0
	s_sub_u32 s3, s3, 0x4600
	s_lshr_b32 s4, s3, 6
	s_and_b32 s5, s3, 63
	s_mul_i32 s6, s0, 0x2c00000
	s_lshl_b32 s7, s4, 19
	s_add_u32 s6, s6, s7
	s_lshl_b32 s7, s5, 7
	s_add_u32 s6, s6, s7
	s_mul_i32 s7, s0, 0x1600000
	s_add_u32 s7, s7, 0x9c00000
	s_mul_i32 s5, s5, 0x58000
	s_add_u32 s7, s7, s5
	s_lshl_b32 s4, s4, 7
	s_add_u32 s7, s7, s4
	s_movk_i32 s38, 0x4000
	s_mov_b32 s42, 0x16000
	s_branch .LitA_p6c

.LitA_p6c:
	s_lshr_b32 s4, s38, 1
	s_lshr_b32 s5, s42, 3
	v_mad_u32_u24 v13, v5, s4, v6
	v_mad_u32_u24 v2, v7, s5, v8
	s_add_u32 s44, s56, s7
	s_addc_u32 s45, s57, 0
	s_waitcnt lgkmcnt(0)
	s_add_u32 s40, s40, s6
	s_addc_u32 s41, s41, 0
	global_load_dword v84, v13, s[40:41] nt
	s_add_u32 s40, s40, s38
	s_addc_u32 s41, s41, 0
	global_load_dword v85, v13, s[40:41] nt
	s_add_u32 s40, s40, s38
	s_addc_u32 s41, s41, 0
	global_load_dword v86, v13, s[40:41] nt
	s_add_u32 s40, s40, s38
	s_addc_u32 s41, s41, 0
	global_load_dword v87, v13, s[40:41] nt
	s_add_u32 s40, s40, s38
	s_addc_u32 s41, s41, 0
	global_load_dword v88, v13, s[40:41] nt
	s_add_u32 s40, s40, s38
	s_addc_u32 s41, s41, 0
	global_load_dword v89, v13, s[40:41] nt
	s_add_u32 s40, s40, s38
	s_addc_u32 s41, s41, 0
	global_load_dword v90, v13, s[40:41] nt
	s_add_u32 s40, s40, s38
	s_addc_u32 s41, s41, 0
	global_load_dword v91, v13, s[40:41] nt
	s_add_u32 s40, s40, s38
	s_addc_u32 s41, s41, 0
	global_load_dword v92, v13, s[40:41] nt
	s_add_u32 s40, s40, s38
	s_addc_u32 s41, s41, 0
	global_load_dword v93, v13, s[40:41] nt
	s_add_u32 s40, s40, s38
	s_addc_u32 s41, s41, 0
	global_load_dword v94, v13, s[40:41] nt
	s_add_u32 s40, s40, s38
	s_addc_u32 s41, s41, 0
	global_load_dword v95, v13, s[40:41] nt
	s_add_u32 s40, s40, s38
	s_addc_u32 s41, s41, 0
	global_load_dword v96, v13, s[40:41] nt
	s_add_u32 s40, s40, s38
	s_addc_u32 s41, s41, 0
	global_load_dword v97, v13, s[40:41] nt
	s_add_u32 s40, s40, s38
	s_addc_u32 s41, s41, 0
	global_load_dword v98, v13, s[40:41] nt
	s_add_u32 s40, s40, s38
	s_addc_u32 s41, s41, 0
	global_load_dword v99, v13, s[40:41] nt
	s_add_u32 s40, s40, s38
	s_addc_u32 s41, s41, 0
	global_load_dword v100, v13, s[40:41] nt
	s_add_u32 s40, s40, s38
	s_addc_u32 s41, s41, 0
	global_load_dword v101, v13, s[40:41] nt
	s_add_u32 s40, s40, s38
	s_addc_u32 s41, s41, 0
	global_load_dword v102, v13, s[40:41] nt
	s_add_u32 s40, s40, s38
	s_addc_u32 s41, s41, 0
	global_load_dword v103, v13, s[40:41] nt
	s_add_u32 s40, s40, s38
	s_addc_u32 s41, s41, 0
	global_load_dword v104, v13, s[40:41] nt
	s_add_u32 s40, s40, s38
	s_addc_u32 s41, s41, 0
	global_load_dword v105, v13, s[40:41] nt
	s_add_u32 s40, s40, s38
	s_addc_u32 s41, s41, 0
	global_load_dword v106, v13, s[40:41] nt
	s_add_u32 s40, s40, s38
	s_addc_u32 s41, s41, 0
	global_load_dword v107, v13, s[40:41] nt
	s_add_u32 s40, s40, s38
	s_addc_u32 s41, s41, 0
	global_load_dword v108, v13, s[40:41] nt
	s_add_u32 s40, s40, s38
	s_addc_u32 s41, s41, 0
	global_load_dword v109, v13, s[40:41] nt
	s_add_u32 s40, s40, s38
	s_addc_u32 s41, s41, 0
	global_load_dword v110, v13, s[40:41] nt
	s_add_u32 s40, s40, s38
	s_addc_u32 s41, s41, 0
	global_load_dword v111, v13, s[40:41] nt
	s_add_u32 s40, s40, s38
	s_addc_u32 s41, s41, 0
	global_load_dword v112, v13, s[40:41] nt
	s_add_u32 s40, s40, s38
	s_addc_u32 s41, s41, 0
	global_load_dword v113, v13, s[40:41] nt
	s_add_u32 s40, s40, s38
	s_addc_u32 s41, s41, 0
	global_load_dword v114, v13, s[40:41] nt
	s_add_u32 s40, s40, s38
	s_addc_u32 s41, s41, 0
	global_load_dword v115, v13, s[40:41] nt
	s_add_i32 s25, s25, s1
	s_branch .LitA_loop
.LitA_dr_p1:
	s_waitcnt vmcnt(0)
	ds_write_b32 v9, v20
	ds_write_b32 v9, v21 offset:264
	ds_write_b32 v9, v22 offset:528
	ds_write_b32 v9, v23 offset:792
	ds_write_b32 v9, v24 offset:1056
	ds_write_b32 v9, v25 offset:1320
	ds_write_b32 v9, v26 offset:1584
	ds_write_b32 v9, v27 offset:1848
	ds_write_b32 v9, v28 offset:2112
	ds_write_b32 v9, v29 offset:2376
	ds_write_b32 v9, v30 offset:2640
	ds_write_b32 v9, v31 offset:2904
	ds_write_b32 v9, v32 offset:3168
	ds_write_b32 v9, v33 offset:3432
	ds_write_b32 v9, v34 offset:3696
	ds_write_b32 v9, v35 offset:3960
	ds_write_b32 v9, v36 offset:4224
	ds_write_b32 v9, v37 offset:4488
	ds_write_b32 v9, v38 offset:4752
	ds_write_b32 v9, v39 offset:5016
	ds_write_b32 v9, v40 offset:5280
	ds_write_b32 v9, v41 offset:5544
	ds_write_b32 v9, v42 offset:5808
	ds_write_b32 v9, v43 offset:6072
	ds_write_b32 v9, v44 offset:6336
	ds_write_b32 v9, v45 offset:6600
	ds_write_b32 v9, v46 offset:6864
	ds_write_b32 v9, v47 offset:7128
	ds_write_b32 v9, v48 offset:7392
	ds_write_b32 v9, v49 offset:7656
	ds_write_b32 v9, v50 offset:7920
	ds_write_b32 v9, v51 offset:8184
	ds_read2_b32 v[116:117], v10 offset0:0 offset1:33
	ds_read2_b32 v[118:119], v10 offset0:66 offset1:99
	ds_read2_b32 v[120:121], v10 offset0:132 offset1:165
	ds_read2_b32 v[122:123], v10 offset0:198 offset1:231
	ds_read2_b32 v[124:125], v10 offset0:8 offset1:41
	ds_read2_b32 v[126:127], v10 offset0:74 offset1:107
	ds_read2_b32 v[128:129], v10 offset0:140 offset1:173
	ds_read2_b32 v[130:131], v10 offset0:206 offset1:239
	ds_read2_b32 v[132:133], v10 offset0:16 offset1:49
	ds_read2_b32 v[134:135], v10 offset0:82 offset1:115
	ds_read2_b32 v[136:137], v10 offset0:148 offset1:181
	ds_read2_b32 v[138:139], v10 offset0:214 offset1:247
	ds_read2_b32 v[140:141], v10 offset0:24 offset1:57
	ds_read2_b32 v[142:143], v10 offset0:90 offset1:123
	ds_read2_b32 v[144:145], v10 offset0:156 offset1:189
	ds_read2_b32 v[146:147], v10 offset0:222 offset1:255
	s_waitcnt lgkmcnt(12)
	v_cvt_pk_bf16_f32 v170, v116, v117
	v_cvt_pk_bf16_f32 v171, v118, v119
	v_cvt_pk_bf16_f32 v172, v120, v121
	v_cvt_pk_bf16_f32 v173, v122, v123
	global_store_dwordx4 v0, v[170:173], s[10:11]
	s_add_u32 s10, s10, s13
	s_addc_u32 s11, s11, 0
	s_waitcnt lgkmcnt(8)
	v_cvt_pk_bf16_f32 v174, v124, v125
	v_cvt_pk_bf16_f32 v175, v126, v127
	v_cvt_pk_bf16_f32 v176, v128, v129
	v_cvt_pk_bf16_f32 v177, v130, v131
	global_store_dwordx4 v0, v[174:177], s[10:11]
	s_add_u32 s10, s10, s13
	s_addc_u32 s11, s11, 0
	s_waitcnt lgkmcnt(4)
	v_cvt_pk_bf16_f32 v178, v132, v133
	v_cvt_pk_bf16_f32 v179, v134, v135
	v_cvt_pk_bf16_f32 v180, v136, v137
	v_cvt_pk_bf16_f32 v181, v138, v139
	global_store_dwordx4 v0, v[178:181], s[10:11]
	s_add_u32 s10, s10, s13
	s_addc_u32 s11, s11, 0
	s_waitcnt lgkmcnt(0)
	v_cvt_pk_bf16_f32 v182, v140, v141
	v_cvt_pk_bf16_f32 v183, v142, v143
	v_cvt_pk_bf16_f32 v184, v144, v145
	v_cvt_pk_bf16_f32 v185, v146, v147
	global_store_dwordx4 v0, v[182:185], s[10:11]
	s_branch .LBB0_219
.LitA_dr_p2:
	s_waitcnt vmcnt(32)
	ds_write_b32 v9, v20
	ds_write_b32 v9, v21 offset:264
	ds_write_b32 v9, v22 offset:528
	ds_write_b32 v9, v23 offset:792
	ds_write_b32 v9, v24 offset:1056
	ds_write_b32 v9, v25 offset:1320
	ds_write_b32 v9, v26 offset:1584
	ds_write_b32 v9, v27 offset:1848
	ds_write_b32 v9, v28 offset:2112
	ds_write_b32 v9, v29 offset:2376
	ds_write_b32 v9, v30 offset:2640
	ds_write_b32 v9, v31 offset:2904
	ds_write_b32 v9, v32 offset:3168
	ds_write_b32 v9, v33 offset:3432
	ds_write_b32 v9, v34 offset:3696
	ds_write_b32 v9, v35 offset:3960
	ds_write_b32 v9, v36 offset:4224
	ds_write_b32 v9, v37 offset:4488
	ds_write_b32 v9, v38 offset:4752
	ds_write_b32 v9, v39 offset:5016
	ds_write_b32 v9, v40 offset:5280
	ds_write_b32 v9, v41 offset:5544
	ds_write_b32 v9, v42 offset:5808
	ds_write_b32 v9, v43 offset:6072
	ds_write_b32 v9, v44 offset:6336
	ds_write_b32 v9, v45 offset:6600
	ds_write_b32 v9, v46 offset:6864
	ds_write_b32 v9, v47 offset:7128
	ds_write_b32 v9, v48 offset:7392
	ds_write_b32 v9, v49 offset:7656
	ds_write_b32 v9, v50 offset:7920
	ds_write_b32 v9, v51 offset:8184
	ds_read2_b32 v[116:117], v10 offset0:0 offset1:33
	ds_read2_b32 v[118:119], v10 offset0:66 offset1:99
	ds_read2_b32 v[120:121], v10 offset0:132 offset1:165
	ds_read2_b32 v[122:123], v10 offset0:198 offset1:231
	ds_read2_b32 v[124:125], v10 offset0:8 offset1:41
	ds_read2_b32 v[126:127], v10 offset0:74 offset1:107
	ds_read2_b32 v[128:129], v10 offset0:140 offset1:173
	ds_read2_b32 v[130:131], v10 offset0:206 offset1:239
	ds_read2_b32 v[132:133], v10 offset0:16 offset1:49
	ds_read2_b32 v[134:135], v10 offset0:82 offset1:115
	ds_read2_b32 v[136:137], v10 offset0:148 offset1:181
	ds_read2_b32 v[138:139], v10 offset0:214 offset1:247
	ds_read2_b32 v[140:141], v10 offset0:24 offset1:57
	ds_read2_b32 v[142:143], v10 offset0:90 offset1:123
	ds_read2_b32 v[144:145], v10 offset0:156 offset1:189
	ds_read2_b32 v[146:147], v10 offset0:222 offset1:255
	s_waitcnt lgkmcnt(12)
	v_cvt_pk_bf16_f32 v170, v116, v117
	v_cvt_pk_bf16_f32 v171, v118, v119
	v_cvt_pk_bf16_f32 v172, v120, v121
	v_cvt_pk_bf16_f32 v173, v122, v123
	global_store_dwordx4 v0, v[170:173], s[10:11]
	s_add_u32 s10, s10, s13
	s_addc_u32 s11, s11, 0
	s_waitcnt lgkmcnt(8)
	v_cvt_pk_bf16_f32 v174, v124, v125
	v_cvt_pk_bf16_f32 v175, v126, v127
	v_cvt_pk_bf16_f32 v176, v128, v129
	v_cvt_pk_bf16_f32 v177, v130, v131
	global_store_dwordx4 v0, v[174:177], s[10:11]
	s_add_u32 s10, s10, s13
	s_addc_u32 s11, s11, 0
	s_waitcnt lgkmcnt(4)
	v_cvt_pk_bf16_f32 v178, v132, v133
	v_cvt_pk_bf16_f32 v179, v134, v135
	v_cvt_pk_bf16_f32 v180, v136, v137
	v_cvt_pk_bf16_f32 v181, v138, v139
	global_store_dwordx4 v0, v[178:181], s[10:11]
	s_add_u32 s10, s10, s13
	s_addc_u32 s11, s11, 0
	s_waitcnt lgkmcnt(0)
	v_cvt_pk_bf16_f32 v182, v140, v141
	v_cvt_pk_bf16_f32 v183, v142, v143
	v_cvt_pk_bf16_f32 v184, v144, v145
	v_cvt_pk_bf16_f32 v185, v146, v147
	global_store_dwordx4 v0, v[182:185], s[10:11]
	s_waitcnt vmcnt(0)
	ds_write_b32 v9, v52
	ds_write_b32 v9, v53 offset:264
	ds_write_b32 v9, v54 offset:528
	ds_write_b32 v9, v55 offset:792
	ds_write_b32 v9, v56 offset:1056
	ds_write_b32 v9, v57 offset:1320
	ds_write_b32 v9, v58 offset:1584
	ds_write_b32 v9, v59 offset:1848
	ds_write_b32 v9, v60 offset:2112
	ds_write_b32 v9, v61 offset:2376
	ds_write_b32 v9, v62 offset:2640
	ds_write_b32 v9, v63 offset:2904
	ds_write_b32 v9, v64 offset:3168
	ds_write_b32 v9, v65 offset:3432
	ds_write_b32 v9, v66 offset:3696
	ds_write_b32 v9, v67 offset:3960
	ds_write_b32 v9, v68 offset:4224
	ds_write_b32 v9, v69 offset:4488
	ds_write_b32 v9, v70 offset:4752
	ds_write_b32 v9, v71 offset:5016
	ds_write_b32 v9, v72 offset:5280
	ds_write_b32 v9, v73 offset:5544
	ds_write_b32 v9, v74 offset:5808
	ds_write_b32 v9, v75 offset:6072
	ds_write_b32 v9, v76 offset:6336
	ds_write_b32 v9, v77 offset:6600
	ds_write_b32 v9, v78 offset:6864
	ds_write_b32 v9, v79 offset:7128
	ds_write_b32 v9, v80 offset:7392
	ds_write_b32 v9, v81 offset:7656
	ds_write_b32 v9, v82 offset:7920
	ds_write_b32 v9, v83 offset:8184
	ds_read2_b32 v[116:117], v10 offset0:0 offset1:33
	ds_read2_b32 v[118:119], v10 offset0:66 offset1:99
	ds_read2_b32 v[120:121], v10 offset0:132 offset1:165
	ds_read2_b32 v[122:123], v10 offset0:198 offset1:231
	ds_read2_b32 v[124:125], v10 offset0:8 offset1:41
	ds_read2_b32 v[126:127], v10 offset0:74 offset1:107
	ds_read2_b32 v[128:129], v10 offset0:140 offset1:173
	ds_read2_b32 v[130:131], v10 offset0:206 offset1:239
	ds_read2_b32 v[132:133], v10 offset0:16 offset1:49
	ds_read2_b32 v[134:135], v10 offset0:82 offset1:115
	ds_read2_b32 v[136:137], v10 offset0:148 offset1:181
	ds_read2_b32 v[138:139], v10 offset0:214 offset1:247
	ds_read2_b32 v[140:141], v10 offset0:24 offset1:57
	ds_read2_b32 v[142:143], v10 offset0:90 offset1:123
	ds_read2_b32 v[144:145], v10 offset0:156 offset1:189
	ds_read2_b32 v[146:147], v10 offset0:222 offset1:255
	s_waitcnt lgkmcnt(12)
	v_cvt_pk_bf16_f32 v170, v116, v117
	v_cvt_pk_bf16_f32 v171, v118, v119
	v_cvt_pk_bf16_f32 v172, v120, v121
	v_cvt_pk_bf16_f32 v173, v122, v123
	global_store_dwordx4 v1, v[170:173], s[36:37]
	s_add_u32 s36, s36, s20
	s_addc_u32 s37, s37, 0
	s_waitcnt lgkmcnt(8)
	v_cvt_pk_bf16_f32 v174, v124, v125
	v_cvt_pk_bf16_f32 v175, v126, v127
	v_cvt_pk_bf16_f32 v176, v128, v129
	v_cvt_pk_bf16_f32 v177, v130, v131
	global_store_dwordx4 v1, v[174:177], s[36:37]
	s_add_u32 s36, s36, s20
	s_addc_u32 s37, s37, 0
	s_waitcnt lgkmcnt(4)
	v_cvt_pk_bf16_f32 v178, v132, v133
	v_cvt_pk_bf16_f32 v179, v134, v135
	v_cvt_pk_bf16_f32 v180, v136, v137
	v_cvt_pk_bf16_f32 v181, v138, v139
	global_store_dwordx4 v1, v[178:181], s[36:37]
	s_add_u32 s36, s36, s20
	s_addc_u32 s37, s37, 0
	s_waitcnt lgkmcnt(0)
	v_cvt_pk_bf16_f32 v182, v140, v141
	v_cvt_pk_bf16_f32 v183, v142, v143
	v_cvt_pk_bf16_f32 v184, v144, v145
	v_cvt_pk_bf16_f32 v185, v146, v147
	global_store_dwordx4 v1, v[182:185], s[36:37]
	s_branch .LBB0_219
.LitA_dr_l0:
	s_waitcnt vmcnt(32)
	ds_write_b32 v9, v52
	ds_write_b32 v9, v53 offset:264
	ds_write_b32 v9, v54 offset:528
	ds_write_b32 v9, v55 offset:792
	ds_write_b32 v9, v56 offset:1056
	ds_write_b32 v9, v57 offset:1320
	ds_write_b32 v9, v58 offset:1584
	ds_write_b32 v9, v59 offset:1848
	ds_write_b32 v9, v60 offset:2112
	ds_write_b32 v9, v61 offset:2376
	ds_write_b32 v9, v62 offset:2640
	ds_write_b32 v9, v63 offset:2904
	ds_write_b32 v9, v64 offset:3168
	ds_write_b32 v9, v65 offset:3432
	ds_write_b32 v9, v66 offset:3696
	ds_write_b32 v9, v67 offset:3960
	ds_write_b32 v9, v68 offset:4224
	ds_write_b32 v9, v69 offset:4488
	ds_write_b32 v9, v70 offset:4752
	ds_write_b32 v9, v71 offset:5016
	ds_write_b32 v9, v72 offset:5280
	ds_write_b32 v9, v73 offset:5544
	ds_write_b32 v9, v74 offset:5808
	ds_write_b32 v9, v75 offset:6072
	ds_write_b32 v9, v76 offset:6336
	ds_write_b32 v9, v77 offset:6600
	ds_write_b32 v9, v78 offset:6864
	ds_write_b32 v9, v79 offset:7128
	ds_write_b32 v9, v80 offset:7392
	ds_write_b32 v9, v81 offset:7656
	ds_write_b32 v9, v82 offset:7920
	ds_write_b32 v9, v83 offset:8184
	ds_read2_b32 v[116:117], v10 offset0:0 offset1:33
	ds_read2_b32 v[118:119], v10 offset0:66 offset1:99
	ds_read2_b32 v[120:121], v10 offset0:132 offset1:165
	ds_read2_b32 v[122:123], v10 offset0:198 offset1:231
	ds_read2_b32 v[124:125], v10 offset0:8 offset1:41
	ds_read2_b32 v[126:127], v10 offset0:74 offset1:107
	ds_read2_b32 v[128:129], v10 offset0:140 offset1:173
	ds_read2_b32 v[130:131], v10 offset0:206 offset1:239
	ds_read2_b32 v[132:133], v10 offset0:16 offset1:49
	ds_read2_b32 v[134:135], v10 offset0:82 offset1:115
	ds_read2_b32 v[136:137], v10 offset0:148 offset1:181
	ds_read2_b32 v[138:139], v10 offset0:214 offset1:247
	ds_read2_b32 v[140:141], v10 offset0:24 offset1:57
	ds_read2_b32 v[142:143], v10 offset0:90 offset1:123
	ds_read2_b32 v[144:145], v10 offset0:156 offset1:189
	ds_read2_b32 v[146:147], v10 offset0:222 offset1:255
	s_waitcnt lgkmcnt(12)
	v_cvt_pk_bf16_f32 v170, v116, v117
	v_cvt_pk_bf16_f32 v171, v118, v119
	v_cvt_pk_bf16_f32 v172, v120, v121
	v_cvt_pk_bf16_f32 v173, v122, v123
	global_store_dwordx4 v1, v[170:173], s[36:37]
	s_add_u32 s36, s36, s20
	s_addc_u32 s37, s37, 0
	s_waitcnt lgkmcnt(8)
	v_cvt_pk_bf16_f32 v174, v124, v125
	v_cvt_pk_bf16_f32 v175, v126, v127
	v_cvt_pk_bf16_f32 v176, v128, v129
	v_cvt_pk_bf16_f32 v177, v130, v131
	global_store_dwordx4 v1, v[174:177], s[36:37]
	s_add_u32 s36, s36, s20
	s_addc_u32 s37, s37, 0
	s_waitcnt lgkmcnt(4)
	v_cvt_pk_bf16_f32 v178, v132, v133
	v_cvt_pk_bf16_f32 v179, v134, v135
	v_cvt_pk_bf16_f32 v180, v136, v137
	v_cvt_pk_bf16_f32 v181, v138, v139
	global_store_dwordx4 v1, v[178:181], s[36:37]
	s_add_u32 s36, s36, s20
	s_addc_u32 s37, s37, 0
	s_waitcnt lgkmcnt(0)
	v_cvt_pk_bf16_f32 v182, v140, v141
	v_cvt_pk_bf16_f32 v183, v142, v143
	v_cvt_pk_bf16_f32 v184, v144, v145
	v_cvt_pk_bf16_f32 v185, v146, v147
	global_store_dwordx4 v1, v[182:185], s[36:37]
	s_waitcnt vmcnt(0)
	ds_write_b32 v9, v84
	ds_write_b32 v9, v85 offset:264
	ds_write_b32 v9, v86 offset:528
	ds_write_b32 v9, v87 offset:792
	ds_write_b32 v9, v88 offset:1056
	ds_write_b32 v9, v89 offset:1320
	ds_write_b32 v9, v90 offset:1584
	ds_write_b32 v9, v91 offset:1848
	ds_write_b32 v9, v92 offset:2112
	ds_write_b32 v9, v93 offset:2376
	ds_write_b32 v9, v94 offset:2640
	ds_write_b32 v9, v95 offset:2904
	ds_write_b32 v9, v96 offset:3168
	ds_write_b32 v9, v97 offset:3432
	ds_write_b32 v9, v98 offset:3696
	ds_write_b32 v9, v99 offset:3960
	ds_write_b32 v9, v100 offset:4224
	ds_write_b32 v9, v101 offset:4488
	ds_write_b32 v9, v102 offset:4752
	ds_write_b32 v9, v103 offset:5016
	ds_write_b32 v9, v104 offset:5280
	ds_write_b32 v9, v105 offset:5544
	ds_write_b32 v9, v106 offset:5808
	ds_write_b32 v9, v107 offset:6072
	ds_write_b32 v9, v108 offset:6336
	ds_write_b32 v9, v109 offset:6600
	ds_write_b32 v9, v110 offset:6864
	ds_write_b32 v9, v111 offset:7128
	ds_write_b32 v9, v112 offset:7392
	ds_write_b32 v9, v113 offset:7656
	ds_write_b32 v9, v114 offset:7920
	ds_write_b32 v9, v115 offset:8184
	ds_read2_b32 v[116:117], v10 offset0:0 offset1:33
	ds_read2_b32 v[118:119], v10 offset0:66 offset1:99
	ds_read2_b32 v[120:121], v10 offset0:132 offset1:165
	ds_read2_b32 v[122:123], v10 offset0:198 offset1:231
	ds_read2_b32 v[124:125], v10 offset0:8 offset1:41
	ds_read2_b32 v[126:127], v10 offset0:74 offset1:107
	ds_read2_b32 v[128:129], v10 offset0:140 offset1:173
	ds_read2_b32 v[130:131], v10 offset0:206 offset1:239
	ds_read2_b32 v[132:133], v10 offset0:16 offset1:49
	ds_read2_b32 v[134:135], v10 offset0:82 offset1:115
	ds_read2_b32 v[136:137], v10 offset0:148 offset1:181
	ds_read2_b32 v[138:139], v10 offset0:214 offset1:247
	ds_read2_b32 v[140:141], v10 offset0:24 offset1:57
	ds_read2_b32 v[142:143], v10 offset0:90 offset1:123
	ds_read2_b32 v[144:145], v10 offset0:156 offset1:189
	ds_read2_b32 v[146:147], v10 offset0:222 offset1:255
	s_waitcnt lgkmcnt(12)
	v_cvt_pk_bf16_f32 v170, v116, v117
	v_cvt_pk_bf16_f32 v171, v118, v119
	v_cvt_pk_bf16_f32 v172, v120, v121
	v_cvt_pk_bf16_f32 v173, v122, v123
	global_store_dwordx4 v2, v[170:173], s[44:45]
	s_add_u32 s44, s44, s42
	s_addc_u32 s45, s45, 0
	s_waitcnt lgkmcnt(8)
	v_cvt_pk_bf16_f32 v174, v124, v125
	v_cvt_pk_bf16_f32 v175, v126, v127
	v_cvt_pk_bf16_f32 v176, v128, v129
	v_cvt_pk_bf16_f32 v177, v130, v131
	global_store_dwordx4 v2, v[174:177], s[44:45]
	s_add_u32 s44, s44, s42
	s_addc_u32 s45, s45, 0
	s_waitcnt lgkmcnt(4)
	v_cvt_pk_bf16_f32 v178, v132, v133
	v_cvt_pk_bf16_f32 v179, v134, v135
	v_cvt_pk_bf16_f32 v180, v136, v137
	v_cvt_pk_bf16_f32 v181, v138, v139
	global_store_dwordx4 v2, v[178:181], s[44:45]
	s_add_u32 s44, s44, s42
	s_addc_u32 s45, s45, 0
	s_waitcnt lgkmcnt(0)
	v_cvt_pk_bf16_f32 v182, v140, v141
	v_cvt_pk_bf16_f32 v183, v142, v143
	v_cvt_pk_bf16_f32 v184, v144, v145
	v_cvt_pk_bf16_f32 v185, v146, v147
	global_store_dwordx4 v2, v[182:185], s[44:45]
	s_branch .LBB0_219
.LitA_dr_l1:
	s_waitcnt vmcnt(32)
	ds_write_b32 v9, v84
	ds_write_b32 v9, v85 offset:264
	ds_write_b32 v9, v86 offset:528
	ds_write_b32 v9, v87 offset:792
	ds_write_b32 v9, v88 offset:1056
	ds_write_b32 v9, v89 offset:1320
	ds_write_b32 v9, v90 offset:1584
	ds_write_b32 v9, v91 offset:1848
	ds_write_b32 v9, v92 offset:2112
	ds_write_b32 v9, v93 offset:2376
	ds_write_b32 v9, v94 offset:2640
	ds_write_b32 v9, v95 offset:2904
	ds_write_b32 v9, v96 offset:3168
	ds_write_b32 v9, v97 offset:3432
	ds_write_b32 v9, v98 offset:3696
	ds_write_b32 v9, v99 offset:3960
	ds_write_b32 v9, v100 offset:4224
	ds_write_b32 v9, v101 offset:4488
	ds_write_b32 v9, v102 offset:4752
	ds_write_b32 v9, v103 offset:5016
	ds_write_b32 v9, v104 offset:5280
	ds_write_b32 v9, v105 offset:5544
	ds_write_b32 v9, v106 offset:5808
	ds_write_b32 v9, v107 offset:6072
	ds_write_b32 v9, v108 offset:6336
	ds_write_b32 v9, v109 offset:6600
	ds_write_b32 v9, v110 offset:6864
	ds_write_b32 v9, v111 offset:7128
	ds_write_b32 v9, v112 offset:7392
	ds_write_b32 v9, v113 offset:7656
	ds_write_b32 v9, v114 offset:7920
	ds_write_b32 v9, v115 offset:8184
	ds_read2_b32 v[116:117], v10 offset0:0 offset1:33
	ds_read2_b32 v[118:119], v10 offset0:66 offset1:99
	ds_read2_b32 v[120:121], v10 offset0:132 offset1:165
	ds_read2_b32 v[122:123], v10 offset0:198 offset1:231
	ds_read2_b32 v[124:125], v10 offset0:8 offset1:41
	ds_read2_b32 v[126:127], v10 offset0:74 offset1:107
	ds_read2_b32 v[128:129], v10 offset0:140 offset1:173
	ds_read2_b32 v[130:131], v10 offset0:206 offset1:239
	ds_read2_b32 v[132:133], v10 offset0:16 offset1:49
	ds_read2_b32 v[134:135], v10 offset0:82 offset1:115
	ds_read2_b32 v[136:137], v10 offset0:148 offset1:181
	ds_read2_b32 v[138:139], v10 offset0:214 offset1:247
	ds_read2_b32 v[140:141], v10 offset0:24 offset1:57
	ds_read2_b32 v[142:143], v10 offset0:90 offset1:123
	ds_read2_b32 v[144:145], v10 offset0:156 offset1:189
	ds_read2_b32 v[146:147], v10 offset0:222 offset1:255
	s_waitcnt lgkmcnt(12)
	v_cvt_pk_bf16_f32 v170, v116, v117
	v_cvt_pk_bf16_f32 v171, v118, v119
	v_cvt_pk_bf16_f32 v172, v120, v121
	v_cvt_pk_bf16_f32 v173, v122, v123
	global_store_dwordx4 v2, v[170:173], s[44:45]
	s_add_u32 s44, s44, s42
	s_addc_u32 s45, s45, 0
	s_waitcnt lgkmcnt(8)
	v_cvt_pk_bf16_f32 v174, v124, v125
	v_cvt_pk_bf16_f32 v175, v126, v127
	v_cvt_pk_bf16_f32 v176, v128, v129
	v_cvt_pk_bf16_f32 v177, v130, v131
	global_store_dwordx4 v2, v[174:177], s[44:45]
	s_add_u32 s44, s44, s42
	s_addc_u32 s45, s45, 0
	s_waitcnt lgkmcnt(4)
	v_cvt_pk_bf16_f32 v178, v132, v133
	v_cvt_pk_bf16_f32 v179, v134, v135
	v_cvt_pk_bf16_f32 v180, v136, v137
	v_cvt_pk_bf16_f32 v181, v138, v139
	global_store_dwordx4 v2, v[178:181], s[44:45]
	s_add_u32 s44, s44, s42
	s_addc_u32 s45, s45, 0
	s_waitcnt lgkmcnt(0)
	v_cvt_pk_bf16_f32 v182, v140, v141
	v_cvt_pk_bf16_f32 v183, v142, v143
	v_cvt_pk_bf16_f32 v184, v144, v145
	v_cvt_pk_bf16_f32 v185, v146, v147
	global_store_dwordx4 v2, v[182:185], s[44:45]
	s_waitcnt vmcnt(0)
	ds_write_b32 v9, v20
	ds_write_b32 v9, v21 offset:264
	ds_write_b32 v9, v22 offset:528
	ds_write_b32 v9, v23 offset:792
	ds_write_b32 v9, v24 offset:1056
	ds_write_b32 v9, v25 offset:1320
	ds_write_b32 v9, v26 offset:1584
	ds_write_b32 v9, v27 offset:1848
	ds_write_b32 v9, v28 offset:2112
	ds_write_b32 v9, v29 offset:2376
	ds_write_b32 v9, v30 offset:2640
	ds_write_b32 v9, v31 offset:2904
	ds_write_b32 v9, v32 offset:3168
	ds_write_b32 v9, v33 offset:3432
	ds_write_b32 v9, v34 offset:3696
	ds_write_b32 v9, v35 offset:3960
	ds_write_b32 v9, v36 offset:4224
	ds_write_b32 v9, v37 offset:4488
	ds_write_b32 v9, v38 offset:4752
	ds_write_b32 v9, v39 offset:5016
	ds_write_b32 v9, v40 offset:5280
	ds_write_b32 v9, v41 offset:5544
	ds_write_b32 v9, v42 offset:5808
	ds_write_b32 v9, v43 offset:6072
	ds_write_b32 v9, v44 offset:6336
	ds_write_b32 v9, v45 offset:6600
	ds_write_b32 v9, v46 offset:6864
	ds_write_b32 v9, v47 offset:7128
	ds_write_b32 v9, v48 offset:7392
	ds_write_b32 v9, v49 offset:7656
	ds_write_b32 v9, v50 offset:7920
	ds_write_b32 v9, v51 offset:8184
	ds_read2_b32 v[116:117], v10 offset0:0 offset1:33
	ds_read2_b32 v[118:119], v10 offset0:66 offset1:99
	ds_read2_b32 v[120:121], v10 offset0:132 offset1:165
	ds_read2_b32 v[122:123], v10 offset0:198 offset1:231
	ds_read2_b32 v[124:125], v10 offset0:8 offset1:41
	ds_read2_b32 v[126:127], v10 offset0:74 offset1:107
	ds_read2_b32 v[128:129], v10 offset0:140 offset1:173
	ds_read2_b32 v[130:131], v10 offset0:206 offset1:239
	ds_read2_b32 v[132:133], v10 offset0:16 offset1:49
	ds_read2_b32 v[134:135], v10 offset0:82 offset1:115
	ds_read2_b32 v[136:137], v10 offset0:148 offset1:181
	ds_read2_b32 v[138:139], v10 offset0:214 offset1:247
	ds_read2_b32 v[140:141], v10 offset0:24 offset1:57
	ds_read2_b32 v[142:143], v10 offset0:90 offset1:123
	ds_read2_b32 v[144:145], v10 offset0:156 offset1:189
	ds_read2_b32 v[146:147], v10 offset0:222 offset1:255
	s_waitcnt lgkmcnt(12)
	v_cvt_pk_bf16_f32 v170, v116, v117
	v_cvt_pk_bf16_f32 v171, v118, v119
	v_cvt_pk_bf16_f32 v172, v120, v121
	v_cvt_pk_bf16_f32 v173, v122, v123
	global_store_dwordx4 v0, v[170:173], s[10:11]
	s_add_u32 s10, s10, s13
	s_addc_u32 s11, s11, 0
	s_waitcnt lgkmcnt(8)
	v_cvt_pk_bf16_f32 v174, v124, v125
	v_cvt_pk_bf16_f32 v175, v126, v127
	v_cvt_pk_bf16_f32 v176, v128, v129
	v_cvt_pk_bf16_f32 v177, v130, v131
	global_store_dwordx4 v0, v[174:177], s[10:11]
	s_add_u32 s10, s10, s13
	s_addc_u32 s11, s11, 0
	s_waitcnt lgkmcnt(4)
	v_cvt_pk_bf16_f32 v178, v132, v133
	v_cvt_pk_bf16_f32 v179, v134, v135
	v_cvt_pk_bf16_f32 v180, v136, v137
	v_cvt_pk_bf16_f32 v181, v138, v139
	global_store_dwordx4 v0, v[178:181], s[10:11]
	s_add_u32 s10, s10, s13
	s_addc_u32 s11, s11, 0
	s_waitcnt lgkmcnt(0)
	v_cvt_pk_bf16_f32 v182, v140, v141
	v_cvt_pk_bf16_f32 v183, v142, v143
	v_cvt_pk_bf16_f32 v184, v144, v145
	v_cvt_pk_bf16_f32 v185, v146, v147
	global_store_dwordx4 v0, v[182:185], s[10:11]
	s_branch .LBB0_219

.LBB0_469:
	s_or_b64 exec, exec, s[8:9]
	s_lshl_b32 s0, s43, 14
	s_add_i32 s34, s0, 0
	s_lshl_b32 s0, s2, 3
	s_add_i32 s12, s43, s0
	s_lshl_b32 s13, s14, 3
	s_cmpk_gt_i32 s14, 0xc0
	s_mov_b64 s[4:5], -1
	s_cbranch_scc0 .LBB0_499
	v_cvt_f32_u32_e32 v0, s13
	s_sub_i32 s0, 0, s13
	v_rcp_iflag_f32_e32 v0, v0
	s_nop 0
	v_mul_f32_e32 v0, 0x4f7ffffe, v0
	v_cvt_u32_f32_e32 v0, v0
	s_nop 0
	v_readfirstlane_b32 s1, v0
	s_mul_i32 s0, s0, s1
	s_mul_hi_u32 s0, s1, s0
	s_add_i32 s1, s1, s0
	s_mul_hi_u32 s0, s1, 0x5000
	s_mul_i32 s1, s0, s13
	s_sub_i32 s1, 0x5000, s1
	s_add_i32 s3, s0, 1
	s_sub_i32 s4, s1, s13
	s_cmp_ge_u32 s1, s13
	s_cselect_b32 s0, s3, s0
	s_cselect_b32 s1, s4, s1
	s_add_i32 s3, s0, 1
	s_cmp_ge_u32 s1, s13
	s_cselect_b32 s0, s3, s0
	v_sub_u32_e64 v0, s0, 16 clamp
	s_cmpk_gt_i32 s12, 0x3ff
	v_readfirstlane_b32 s1, v0
	s_mov_b64 s[4:5], -1
	s_cbranch_scc1 .LBB0_473
	s_andn2_b64 vcc, exec, s[4:5]
	s_cbranch_vccz .LBB0_474

.LBB0_473:
	s_add_i32 s0, s13, 0xfffffc00
	s_abs_i32 s3, s0
	v_cvt_f32_u32_e32 v0, s3
	s_mul_i32 s4, s1, 0x400
	s_waitcnt lgkmcnt(0)
	s_sub_i32 s6, 0, s3
	s_sub_i32 s5, s13, s4
	v_rcp_iflag_f32_e32 v0, v0
	s_addk_i32 s5, 0xbff
	s_xor_b32 s0, s5, s0
	s_abs_i32 s5, s5
	v_mul_f32_e32 v0, 0x4f7ffffe, v0
	v_cvt_u32_f32_e32 v0, v0
	s_ashr_i32 s0, s0, 31
	v_readfirstlane_b32 s7, v0
	s_mul_i32 s6, s6, s7
	s_mul_hi_u32 s6, s7, s6
	s_add_i32 s7, s7, s6
	s_mul_hi_u32 s6, s5, s7
	s_mul_i32 s7, s6, s3
	s_sub_i32 s5, s5, s7
	s_add_i32 s8, s6, 1
	s_sub_i32 s7, s5, s3
	s_cmp_ge_u32 s5, s3
	s_cselect_b32 s6, s8, s6
	s_cselect_b32 s5, s7, s5
	s_add_i32 s7, s6, 1
	s_cmp_ge_u32 s5, s3
	s_cselect_b32 s3, s7, s6
	s_xor_b32 s3, s3, s0
	s_sub_i32 s0, s3, s0
	s_add_i32 s3, s12, 0xfffffc00
	s_mul_i32 s3, s0, s3
	s_add_i32 s3, s3, s4
	s_add_i32 s0, s3, s0
	s_min_i32 s8, s0, 0x1000
	s_cbranch_execnz .LBB0_472
.LBB0_474:
	s_lshl_b32 s0, s12, 8
	s_waitcnt lgkmcnt(0)
	s_load_dwordx4 s[4:7], s[58:59], 0x18
	s_load_dwordx2 s[8:9], s[58:59], 0x28
	s_and_b32 s3, s0, 0x700
	v_or_b32_e32 v1, s3, v168
	v_lshlrev_b32_e32 v5, 2, v1
	s_waitcnt lgkmcnt(0)
	global_load_dword v12, v5, s[6:7]
	s_or_b32 s0, s0, 0xfffff800
	v_or_b32_e32 v0, s0, v168
	v_ashrrev_i32_e32 v1, 31, v0
	v_lshl_add_u64 v[6:7], v[0:1], 2, s[4:5]
	v_add_co_u32_e32 v2, vcc, s91, v6
	s_ashr_i32 s0, s0, 31
	s_nop 0
	v_addc_co_u32_e32 v3, vcc, 0, v7, vcc
	v_add_co_u32_e32 v8, vcc, s96, v6
	v_mov_b32_e32 v1, s0
	s_nop 0
	v_addc_co_u32_e32 v9, vcc, 0, v7, vcc
	v_add_co_u32_e32 v10, vcc, s97, v6
	v_lshl_add_u64 v[0:1], v[0:1], 2, s[4:5]
	s_nop 0
	v_addc_co_u32_e32 v11, vcc, 0, v7, vcc
	global_load_dword v20, v[2:3], off
	global_load_dword v21, v[8:9], off
	global_load_dword v22, v[10:11], off
	v_add_co_u32_e32 v2, vcc, s48, v6
	s_ashr_i32 s3, s12, 3
	s_nop 0
	v_addc_co_u32_e32 v3, vcc, 0, v7, vcc
	global_load_dword v3, v[2:3], off
	v_add_co_u32_e32 v8, vcc, s49, v6
	s_mul_hi_i32 s10, s3, 0x2aaaaaab
	s_nop 0
	v_addc_co_u32_e32 v9, vcc, 0, v7, vcc
	global_load_dword v24, v[8:9], off
	v_add_co_u32_e32 v8, vcc, s50, v6
	v_lshl_add_u32 v2, v168, 2, s34
	s_nop 0
	v_addc_co_u32_e32 v9, vcc, 0, v7, vcc
	global_load_dword v25, v[8:9], off
	v_add_co_u32_e32 v8, vcc, s51, v6
	s_lshr_b32 s11, s10, 31
	s_nop 0
	v_addc_co_u32_e32 v9, vcc, 0, v7, vcc
	v_add_co_u32_e32 v6, vcc, s94, v6
	global_load_dword v26, v[8:9], off
	s_nop 0
	v_addc_co_u32_e32 v7, vcc, 0, v7, vcc
	global_load_dword v27, v[6:7], off
	global_load_dword v28, v5, s[6:7] offset:256
	global_load_dword v29, v5, s[6:7] offset:512
	s_nop 0
	global_load_dword v5, v5, s[6:7] offset:768
	v_add_co_u32_e32 v6, vcc, s91, v0
	s_lshr_b32 s10, s10, 4
	s_nop 0
	v_addc_co_u32_e32 v7, vcc, 0, v1, vcc
	v_add_co_u32_e32 v8, vcc, s96, v0
	s_add_i32 s10, s10, s11
	s_nop 0
	v_addc_co_u32_e32 v9, vcc, 0, v1, vcc
	v_add_co_u32_e32 v10, vcc, s97, v0
	s_mulk_i32 s10, 0x60
	s_nop 0
	v_addc_co_u32_e32 v11, vcc, 0, v1, vcc
	global_load_dword v30, v[6:7], off offset:256
	global_load_dword v31, v[8:9], off offset:256
	global_load_dword v32, v[10:11], off offset:256
	s_mul_hi_i32 s0, s12, 0x2aaaaaab
	s_sub_i32 s3, s3, s10
	s_lshr_b32 s4, s0, 31
	s_ashr_i32 s0, s0, 7
	s_add_i32 s0, s0, s4
	s_lshl_b32 s4, s3, 7
	s_and_b32 s7, s12, 7
	s_ashr_i32 s5, s4, 31
	s_mul_i32 s6, s0, 0x6000000
	s_mul_i32 s7, s7, 0xc00000
	s_mul_hi_i32 s3, s0, 0x6000000
	s_add_u32 s6, s6, s7
	s_addc_u32 s3, s3, 0
	s_lshl_b64 s[4:5], s[4:5], 2
	s_waitcnt vmcnt(0)
	v_mul_f32_e32 v13, 0xbfb8aa3b, v12
	v_exp_f32_e32 v13, v13
	s_add_u32 s7, s8, s4
	s_addc_u32 s8, s9, s5
	s_add_u32 s6, s7, s6
	v_add_f32_e32 v13, 1.0, v13
	v_rcp_f32_e32 v13, v13
	s_addc_u32 s7, s8, s3
	s_mov_b32 s3, -8
	global_load_dword v46, v[6:7], off offset:512
	global_load_dword v47, v[8:9], off offset:512
	v_mul_f32_e32 v35, v12, v13
	v_add_co_u32_e32 v12, vcc, s48, v0
	v_mul_f32_e32 v18, 0xbfb8aa3b, v20
	s_nop 0
	v_addc_co_u32_e32 v13, vcc, 0, v1, vcc
	global_load_dword v37, v[12:13], off offset:256
	v_exp_f32_e32 v18, v18
	v_mul_f32_e32 v19, 0xbfb8aa3b, v21
	v_exp_f32_e32 v19, v19
	v_mul_f32_e32 v23, 0xbfb8aa3b, v22
	v_add_f32_e32 v18, 1.0, v18
	v_mul_f32_e32 v36, 0xbfb8aa3b, v3
	v_rcp_f32_e32 v33, v18
	v_exp_f32_e32 v36, v36
	v_add_f32_e32 v19, 1.0, v19
	v_add_co_u32_e32 v18, vcc, s49, v0
	v_exp_f32_e32 v23, v23
	v_rcp_f32_e32 v34, v19
	v_addc_co_u32_e32 v19, vcc, 0, v1, vcc
	v_mul_f32_e32 v33, v20, v33
	v_add_f32_e32 v20, 1.0, v36
	v_mul_f32_e32 v42, 0xbfb8aa3b, v24
	global_load_dword v38, v[18:19], off offset:256
	v_rcp_f32_e32 v36, v20
	v_exp_f32_e32 v42, v42
	v_add_f32_e32 v23, 1.0, v23
	v_rcp_f32_e32 v23, v23
	v_mul_f32_e32 v3, v3, v36
	v_add_f32_e32 v36, 1.0, v42
	v_mul_f32_e32 v42, 0xbfb8aa3b, v25
	v_exp_f32_e32 v42, v42
	v_add_co_u32_e32 v20, vcc, s50, v0
	v_mul_f32_e32 v34, v21, v34
	s_nop 0
	v_addc_co_u32_e32 v21, vcc, 0, v1, vcc
	v_mul_f32_e32 v39, v22, v23
	v_add_co_u32_e32 v22, vcc, s51, v0
	global_load_dword v40, v[20:21], off offset:256
	s_nop 0
	v_addc_co_u32_e32 v23, vcc, 0, v1, vcc
	v_add_f32_e32 v42, 1.0, v42
	global_load_dword v41, v[22:23], off offset:256
	v_rcp_f32_e32 v42, v42
	v_mul_f32_e32 v45, 0xbfb8aa3b, v27
	v_exp_f32_e32 v45, v45
	v_add_co_u32_e32 v0, vcc, s94, v0
	v_mul_f32_e32 v25, v25, v42
	s_nop 0
	v_addc_co_u32_e32 v1, vcc, 0, v1, vcc
	v_mul_f32_e32 v42, 0xbfb8aa3b, v28
	global_load_dword v43, v[0:1], off offset:256
	v_rcp_f32_e32 v36, v36
	v_add_f32_e32 v45, 1.0, v45
	v_exp_f32_e32 v42, v42
	v_rcp_f32_e32 v45, v45
	v_mul_f32_e32 v24, v24, v36
	global_load_dword v36, v[10:11], off offset:512
	s_nop 0
	global_load_dword v8, v[8:9], off offset:768
	s_nop 0
	global_load_dword v6, v[6:7], off offset:768
	v_mul_f32_e32 v7, 0xbfb8aa3b, v30
	v_add_f32_e32 v42, 1.0, v42
	v_mul_f32_e32 v27, v27, v45
	v_exp_f32_e32 v7, v7
	v_rcp_f32_e32 v42, v42
	v_mul_f32_e32 v45, 0xbfb8aa3b, v31
	v_exp_f32_e32 v45, v45
	v_mul_f32_e32 v44, 0xbfb8aa3b, v26
	v_exp_f32_e32 v44, v44
	v_add_f32_e32 v7, 1.0, v7
	v_mul_f32_e32 v28, v28, v42
	v_rcp_f32_e32 v7, v7
	ds_write2st64_b32 v2, v35, v28 offset1:1
	v_add_f32_e32 v28, 1.0, v45
	v_rcp_f32_e32 v28, v28
	v_add_f32_e32 v44, 1.0, v44
	v_rcp_f32_e32 v44, v44
	v_mul_f32_e32 v7, v30, v7
	ds_write2st64_b32 v2, v33, v7 offset0:4 offset1:5
	v_mul_f32_e32 v7, v31, v28
	v_mul_f32_e32 v35, 0xbfb8aa3b, v32
	ds_write2st64_b32 v2, v34, v7 offset0:8 offset1:9
	v_mul_f32_e32 v26, v26, v44
	global_load_dword v9, v[12:13], off offset:512
	global_load_dword v44, v[18:19], off offset:512
	global_load_dword v48, v[20:21], off offset:512
	global_load_dword v30, v[22:23], off offset:512
	global_load_dword v42, v[0:1], off offset:512
	v_exp_f32_e32 v35, v35
	global_load_dword v18, v[18:19], off offset:768
	s_nop 0
	global_load_dword v12, v[12:13], off offset:768
	s_nop 0
	global_load_dword v10, v[10:11], off offset:768
	s_waitcnt vmcnt(15)
	v_mul_f32_e32 v11, 0xbfb8aa3b, v37
	v_exp_f32_e32 v11, v11
	v_add_f32_e32 v7, 1.0, v35
	v_rcp_f32_e32 v7, v7
	v_add_f32_e32 v11, 1.0, v11
	v_rcp_f32_e32 v11, v11
	v_mul_f32_e32 v7, v32, v7
	ds_write2st64_b32 v2, v39, v7 offset0:12 offset1:13
	v_mul_f32_e32 v7, v37, v11
	ds_write2st64_b32 v2, v3, v7 offset0:16 offset1:17
	global_load_dword v0, v[0:1], off offset:768
	s_nop 0
	global_load_dword v1, v[22:23], off offset:768
	global_load_dword v11, v[20:21], off offset:768
	s_waitcnt vmcnt(17)
	v_mul_f32_e32 v13, 0xbfb8aa3b, v38
	v_exp_f32_e32 v13, v13
	s_waitcnt vmcnt(16)
	v_mul_f32_e32 v7, 0xbfb8aa3b, v40
	v_add_f32_e32 v13, 1.0, v13
	v_rcp_f32_e32 v13, v13
	v_exp_f32_e32 v7, v7
	v_mul_f32_e32 v3, v38, v13
	s_waitcnt vmcnt(15)
	v_mul_f32_e32 v13, 0xbfb8aa3b, v41
	v_exp_f32_e32 v13, v13
	ds_write2st64_b32 v2, v24, v3 offset0:20 offset1:21
	v_add_f32_e32 v3, 1.0, v7
	v_rcp_f32_e32 v3, v3
	v_add_f32_e32 v7, 1.0, v13
	v_rcp_f32_e32 v7, v7
	s_waitcnt vmcnt(14)
	v_mul_f32_e32 v13, 0xbfb8aa3b, v43
	v_exp_f32_e32 v13, v13
	v_mul_f32_e32 v24, 0xbfb8aa3b, v5
	v_mul_f32_e32 v3, v40, v3
	v_exp_f32_e32 v24, v24
	ds_write2st64_b32 v2, v25, v3 offset0:24 offset1:25
	v_mul_f32_e32 v3, v41, v7
	v_add_f32_e32 v7, 1.0, v13
	v_rcp_f32_e32 v7, v7
	v_mul_f32_e32 v13, 0xbfb8aa3b, v29
	v_exp_f32_e32 v13, v13
	v_add_f32_e32 v24, 1.0, v24
	s_waitcnt vmcnt(11)
	v_mul_f32_e32 v25, 0xbfb8aa3b, v6
	v_rcp_f32_e32 v24, v24
	v_exp_f32_e32 v25, v25
	ds_write2st64_b32 v2, v26, v3 offset0:28 offset1:29
	v_mul_f32_e32 v3, v43, v7
	v_mul_f32_e32 v7, 0xbfb8aa3b, v46
	ds_write2st64_b32 v2, v27, v3 offset0:32 offset1:33
	v_add_f32_e32 v3, 1.0, v13
	v_exp_f32_e32 v7, v7
	v_mul_f32_e32 v13, 0xbfb8aa3b, v47
	v_mul_f32_e32 v26, 0xbfb8aa3b, v8
	v_exp_f32_e32 v13, v13
	v_rcp_f32_e32 v3, v3
	v_exp_f32_e32 v26, v26
	v_mul_f32_e32 v5, v5, v24
	v_add_f32_e32 v24, 1.0, v25
	v_rcp_f32_e32 v24, v24
	v_add_f32_e32 v7, 1.0, v7
	v_rcp_f32_e32 v7, v7
	v_add_f32_e32 v13, 1.0, v13
	v_mul_f32_e32 v3, v29, v3
	v_add_f32_e32 v25, 1.0, v26
	v_rcp_f32_e32 v13, v13
	v_mul_f32_e32 v19, 0xbfb8aa3b, v36
	v_rcp_f32_e32 v25, v25
	ds_write2st64_b32 v2, v3, v5 offset0:2 offset1:3
	s_waitcnt vmcnt(3)
	v_mul_f32_e32 v5, 0xbfb8aa3b, v10
	v_exp_f32_e32 v19, v19
	v_mul_f32_e32 v3, v6, v24
	v_exp_f32_e32 v5, v5
	v_mul_f32_e32 v6, 0xbfb8aa3b, v12
	v_exp_f32_e32 v6, v6
	v_mul_f32_e32 v7, v46, v7
	v_mul_f32_e32 v13, v47, v13
	ds_write2st64_b32 v2, v7, v3 offset0:6 offset1:7
	v_mul_f32_e32 v3, v8, v25
	v_add_f32_e32 v19, 1.0, v19
	v_mul_f32_e32 v20, 0xbfb8aa3b, v9
	ds_write2st64_b32 v2, v13, v3 offset0:10 offset1:11
	v_add_f32_e32 v3, 1.0, v5
	v_exp_f32_e32 v20, v20
	v_mul_f32_e32 v21, 0xbfb8aa3b, v44
	v_rcp_f32_e32 v19, v19
	v_rcp_f32_e32 v3, v3
	v_add_f32_e32 v5, 1.0, v6
	v_mul_f32_e32 v6, 0xbfb8aa3b, v18
	v_exp_f32_e32 v21, v21
	v_rcp_f32_e32 v5, v5
	v_exp_f32_e32 v6, v6
	v_add_f32_e32 v20, 1.0, v20
	v_mul_f32_e32 v19, v36, v19
	v_mul_f32_e32 v3, v10, v3
	v_rcp_f32_e32 v20, v20
	v_add_f32_e32 v21, 1.0, v21
	ds_write2st64_b32 v2, v19, v3 offset0:14 offset1:15
	v_mul_f32_e32 v3, v12, v5
	v_add_f32_e32 v5, 1.0, v6
	v_rcp_f32_e32 v21, v21
	v_mul_f32_e32 v22, 0xbfb8aa3b, v48
	v_rcp_f32_e32 v5, v5
	s_waitcnt vmcnt(0)
	v_mul_f32_e32 v6, 0xbfb8aa3b, v11
	v_exp_f32_e32 v22, v22
	v_exp_f32_e32 v6, v6
	v_mul_f32_e32 v9, v9, v20
	v_mul_f32_e32 v20, v44, v21
	ds_write2st64_b32 v2, v9, v3 offset0:18 offset1:19
	v_mul_f32_e32 v3, v18, v5
	v_add_f32_e32 v21, 1.0, v22
	v_mul_f32_e32 v22, 0xbfb8aa3b, v30
	v_mul_f32_e32 v23, 0xbfb8aa3b, v42
	ds_write2st64_b32 v2, v20, v3 offset0:22 offset1:23
	v_add_f32_e32 v3, 1.0, v6
	v_mul_f32_e32 v5, 0xbfb8aa3b, v1
	v_mul_f32_e32 v6, 0xbfb8aa3b, v0
	v_exp_f32_e32 v22, v22
	v_exp_f32_e32 v23, v23
	v_exp_f32_e32 v5, v5
	v_exp_f32_e32 v6, v6
	v_add_f32_e32 v22, 1.0, v22
	v_add_f32_e32 v23, 1.0, v23
	v_add_f32_e32 v5, 1.0, v5
	v_add_f32_e32 v6, 1.0, v6
	v_rcp_f32_e32 v21, v21
	v_rcp_f32_e32 v22, v22
	v_rcp_f32_e32 v23, v23
	v_rcp_f32_e32 v3, v3
	v_rcp_f32_e32 v5, v5
	v_rcp_f32_e32 v6, v6
	v_mul_f32_e32 v21, v48, v21
	v_mul_f32_e32 v22, v30, v22
	v_mul_f32_e32 v23, v42, v23
	v_mul_f32_e32 v3, v11, v3
	v_mul_f32_e32 v1, v1, v5
	v_mul_f32_e32 v0, v0, v6
	ds_write2st64_b32 v2, v21, v3 offset0:26 offset1:27
	ds_write2st64_b32 v2, v22, v1 offset0:30 offset1:31
	ds_write2st64_b32 v2, v23, v0 offset0:34 offset1:35
	s_waitcnt lgkmcnt(0)
	v_lshlrev_b32_e32 v0, 3, v168
	v_mov_b32_e32 v1, v4
	v_lshl_add_u64 v[2:3], s[6:7], 0, v[0:1]
	v_mov_b32_e32 v6, 0
	v_lshl_add_u64 v[2:3], v[2:3], 0, s[52:53]
	s_mov_b32 s6, s34
	v_mov_b32_e32 v7, v6
	v_mov_b32_e32 v8, v6
	v_mov_b32_e32 v9, v6
	v_mov_b32_e32 v10, v6
	v_mov_b32_e32 v11, v6
	v_mov_b32_e32 v12, v6
	v_mov_b32_e32 v13, v6
	v_mov_b32_e32 v18, v6
	v_mov_b32_e32 v19, v6
	v_mov_b32_e32 v20, v6
	v_mov_b32_e32 v21, v6
	v_mov_b32_e32 v22, v6
	v_mov_b32_e32 v23, v6
	v_mov_b32_e32 v24, v6
	v_mov_b32_e32 v25, v6
	v_mov_b32_e32 v26, v6
	v_mov_b32_e32 v27, v6
	v_add_co_u32_e32 v28, vcc, s28, v2
	s_nop 0
	v_addc_co_u32_e32 v29, vcc, -1, v3, vcc
	global_load_dwordx2 v[52:53], v[28:29], off nt
	v_add_co_u32_e32 v28, vcc, s29, v2
	s_nop 0
	v_addc_co_u32_e32 v29, vcc, -1, v3, vcc
	global_load_dwordx2 v[54:55], v[28:29], off nt
	v_add_co_u32_e32 v28, vcc, s22, v2
	s_nop 0
	v_addc_co_u32_e32 v29, vcc, -1, v3, vcc
	global_load_dwordx2 v[56:57], v[28:29], off nt
	v_add_co_u32_e32 v28, vcc, s23, v2
	s_nop 0
	v_addc_co_u32_e32 v29, vcc, -1, v3, vcc
	global_load_dwordx2 v[58:59], v[28:29], off nt
	v_add_co_u32_e32 v28, vcc, s26, v2
	s_nop 1
	v_addc_co_u32_e32 v29, vcc, -1, v3, vcc
	global_load_dwordx2 v[60:61], v[28:29], off nt
	v_add_co_u32_e32 v28, vcc, s27, v2
	s_nop 1
	v_addc_co_u32_e32 v29, vcc, -1, v3, vcc
	global_load_dwordx2 v[62:63], v[28:29], off nt
	v_add_co_u32_e32 v28, vcc, s95, v2
	s_nop 1
	v_addc_co_u32_e32 v29, vcc, -1, v3, vcc
	global_load_dwordx2 v[64:65], v[28:29], off nt
	global_load_dwordx2 v[66:67], v[2:3], off nt
.LBB0_475:
	v_lshl_add_u64 v[2:3], v[2:3], 0, s[54:55]
	v_add_co_u32_e32 v28, vcc, s28, v2
	s_nop 0
	v_addc_co_u32_e32 v29, vcc, -1, v3, vcc
	global_load_dwordx2 v[84:85], v[28:29], off nt
	v_add_co_u32_e32 v28, vcc, s29, v2
	s_nop 0
	v_addc_co_u32_e32 v29, vcc, -1, v3, vcc
	global_load_dwordx2 v[86:87], v[28:29], off nt
	v_add_co_u32_e32 v28, vcc, s22, v2
	s_nop 0
	v_addc_co_u32_e32 v29, vcc, -1, v3, vcc
	global_load_dwordx2 v[88:89], v[28:29], off nt
	v_add_co_u32_e32 v28, vcc, s23, v2
	s_nop 0
	v_addc_co_u32_e32 v29, vcc, -1, v3, vcc
	global_load_dwordx2 v[90:91], v[28:29], off nt
	v_add_co_u32_e32 v28, vcc, s26, v2
	s_nop 1
	v_addc_co_u32_e32 v29, vcc, -1, v3, vcc
	global_load_dwordx2 v[92:93], v[28:29], off nt
	v_add_co_u32_e32 v28, vcc, s27, v2
	s_nop 1
	v_addc_co_u32_e32 v29, vcc, -1, v3, vcc
	global_load_dwordx2 v[94:95], v[28:29], off nt
	v_add_co_u32_e32 v28, vcc, s95, v2
	s_nop 1
	v_addc_co_u32_e32 v29, vcc, -1, v3, vcc
	global_load_dwordx2 v[96:97], v[28:29], off nt
	global_load_dwordx2 v[98:99], v[2:3], off nt
	v_mov_b32_e32 v5, s6
	s_add_i32 s6, s6, 32
	ds_read_b128 v[28:31], v5
	ds_read_b128 v[32:35], v5 offset:16
	ds_read_b128 v[36:39], v5 offset:1024
	ds_read_b128 v[40:43], v5 offset:3072
	ds_read_b128 v[44:47], v5 offset:5120
	ds_read_b128 v[48:51], v5 offset:7168
	s_waitcnt vmcnt(15) lgkmcnt(5)
	v_pk_fma_f32 v[68:69], v[52:53], v[28:29], v[6:7] op_sel_hi:[1,0,1]
	s_waitcnt lgkmcnt(3)
	v_pk_fma_f32 v[70:71], v[52:53], v[36:37], v[8:9] op_sel_hi:[1,0,1]
	ds_read_b128 v[6:9], v5 offset:2048
	s_waitcnt lgkmcnt(3)
	v_pk_fma_f32 v[74:75], v[52:53], v[40:41], v[12:13] op_sel_hi:[1,0,1]
	s_waitcnt lgkmcnt(2)
	v_pk_fma_f32 v[78:79], v[52:53], v[44:45], v[20:21] op_sel_hi:[1,0,1]
	s_waitcnt lgkmcnt(1)
	v_pk_fma_f32 v[82:83], v[52:53], v[48:49], v[24:25] op_sel_hi:[1,0,1]
	s_waitcnt vmcnt(14)
	v_pk_fma_f32 v[28:29], v[54:55], v[28:29], v[68:69] op_sel:[0,1,0]
	s_waitcnt lgkmcnt(0)
	v_pk_fma_f32 v[72:73], v[52:53], v[6:7], v[10:11] op_sel_hi:[1,0,1]
	ds_read_b128 v[10:13], v5 offset:4096
	v_pk_fma_f32 v[6:7], v[54:55], v[6:7], v[72:73] op_sel:[0,1,0]
	v_pk_fma_f32 v[36:37], v[54:55], v[36:37], v[70:71] op_sel:[0,1,0]
	v_pk_fma_f32 v[40:41], v[54:55], v[40:41], v[74:75] op_sel:[0,1,0]
	s_waitcnt vmcnt(13)
	v_pk_fma_f32 v[6:7], v[56:57], v[8:9], v[6:7] op_sel_hi:[1,0,1]
	s_waitcnt lgkmcnt(0)
	v_pk_fma_f32 v[76:77], v[52:53], v[10:11], v[18:19] op_sel_hi:[1,0,1]
	ds_read_b128 v[18:21], v5 offset:6144
	v_mov_b32_e32 v8, v31
	v_pk_fma_f32 v[10:11], v[54:55], v[10:11], v[76:77] op_sel:[0,1,0]
	v_pk_fma_f32 v[44:45], v[54:55], v[44:45], v[78:79] op_sel:[0,1,0]
	v_pk_fma_f32 v[10:11], v[56:57], v[12:13], v[10:11] op_sel_hi:[1,0,1]
	s_waitcnt lgkmcnt(0)
	v_pk_fma_f32 v[80:81], v[52:53], v[18:19], v[22:23] op_sel_hi:[1,0,1]
	ds_read_b128 v[22:25], v5 offset:8192
	v_pk_fma_f32 v[18:19], v[54:55], v[18:19], v[80:81] op_sel:[0,1,0]
	v_pk_fma_f32 v[48:49], v[54:55], v[48:49], v[82:83] op_sel:[0,1,0]
	v_pk_fma_f32 v[18:19], v[56:57], v[20:21], v[18:19] op_sel_hi:[1,0,1]
	s_waitcnt lgkmcnt(0)
	v_pk_fma_f32 v[26:27], v[52:53], v[22:23], v[26:27] op_sel_hi:[1,0,1]
	s_nop 0
	v_pk_fma_f32 v[22:23], v[54:55], v[22:23], v[26:27] op_sel:[0,1,0]
	v_pk_fma_f32 v[26:27], v[56:57], v[30:31], v[28:29] op_sel_hi:[1,0,1]
	v_pk_fma_f32 v[28:29], v[56:57], v[38:39], v[36:37] op_sel_hi:[1,0,1]
	s_waitcnt vmcnt(12)
	v_pk_fma_f32 v[26:27], v[58:59], v[8:9], v[26:27] op_sel_hi:[1,0,1]
	v_mov_b32_e32 v8, v39
	v_pk_fma_f32 v[28:29], v[58:59], v[8:9], v[28:29] op_sel_hi:[1,0,1]
	v_mov_b32_e32 v8, v9
	v_pk_fma_f32 v[36:37], v[56:57], v[42:43], v[40:41] op_sel_hi:[1,0,1]
	v_pk_fma_f32 v[30:31], v[58:59], v[8:9], v[6:7] op_sel_hi:[1,0,1]
	v_mov_b32_e32 v6, v43
	v_pk_fma_f32 v[36:37], v[58:59], v[6:7], v[36:37] op_sel_hi:[1,0,1]
	v_mov_b32_e32 v6, v13
	v_pk_fma_f32 v[40:41], v[56:57], v[46:47], v[44:45] op_sel_hi:[1,0,1]
	v_pk_fma_f32 v[38:39], v[58:59], v[6:7], v[10:11] op_sel_hi:[1,0,1]
	v_mov_b32_e32 v6, v47
	v_pk_fma_f32 v[40:41], v[58:59], v[6:7], v[40:41] op_sel_hi:[1,0,1]
	v_mov_b32_e32 v6, v21
	v_pk_fma_f32 v[44:45], v[56:57], v[50:51], v[48:49] op_sel_hi:[1,0,1]
	v_pk_fma_f32 v[42:43], v[58:59], v[6:7], v[18:19] op_sel_hi:[1,0,1]
	v_mov_b32_e32 v6, v51
	v_pk_fma_f32 v[22:23], v[56:57], v[24:25], v[22:23] op_sel_hi:[1,0,1]
	v_pk_fma_f32 v[44:45], v[58:59], v[6:7], v[44:45] op_sel_hi:[1,0,1]
	v_mov_b32_e32 v6, v25
	v_pk_fma_f32 v[48:49], v[58:59], v[6:7], v[22:23] op_sel_hi:[1,0,1]
	ds_read_b128 v[6:9], v5 offset:1040
	ds_read_b128 v[10:13], v5 offset:2064
	ds_read_b128 v[18:21], v5 offset:3088
	ds_read_b128 v[22:25], v5 offset:4112
	s_waitcnt vmcnt(11)
	v_pk_fma_f32 v[50:51], v[60:61], v[32:33], v[26:27] op_sel_hi:[1,0,1]
	s_waitcnt lgkmcnt(3)
	v_pk_fma_f32 v[52:53], v[60:61], v[6:7], v[28:29] op_sel_hi:[1,0,1]
	ds_read_b128 v[26:29], v5 offset:5136
	s_waitcnt lgkmcnt(2)
	v_pk_fma_f32 v[54:55], v[60:61], v[18:19], v[36:37] op_sel_hi:[1,0,1]
	s_waitcnt lgkmcnt(1)
	v_pk_fma_f32 v[56:57], v[60:61], v[22:23], v[38:39] op_sel_hi:[1,0,1]
	ds_read_b128 v[36:39], v5 offset:6160
	v_pk_fma_f32 v[30:31], v[60:61], v[10:11], v[30:31] op_sel_hi:[1,0,1]
	s_waitcnt lgkmcnt(1)
	v_pk_fma_f32 v[58:59], v[60:61], v[26:27], v[40:41] op_sel_hi:[1,0,1]
	s_waitcnt vmcnt(10)
	v_pk_fma_f32 v[10:11], v[62:63], v[10:11], v[30:31] op_sel:[0,1,0]
	v_pk_fma_f32 v[18:19], v[62:63], v[18:19], v[54:55] op_sel:[0,1,0]
	s_waitcnt lgkmcnt(0)
	v_pk_fma_f32 v[68:69], v[60:61], v[36:37], v[42:43] op_sel_hi:[1,0,1]
	ds_read_b128 v[40:43], v5 offset:7184
	s_waitcnt vmcnt(9)
	v_pk_fma_f32 v[10:11], v[64:65], v[12:13], v[10:11] op_sel_hi:[1,0,1]
	v_mov_b32_e32 v12, v13
	v_pk_fma_f32 v[22:23], v[62:63], v[22:23], v[56:57] op_sel:[0,1,0]
	v_pk_fma_f32 v[26:27], v[62:63], v[26:27], v[58:59] op_sel:[0,1,0]
	s_waitcnt lgkmcnt(0)
	v_pk_fma_f32 v[70:71], v[60:61], v[40:41], v[44:45] op_sel_hi:[1,0,1]
	ds_read_b128 v[44:47], v5 offset:8208
	v_pk_fma_f32 v[18:19], v[64:65], v[20:21], v[18:19] op_sel_hi:[1,0,1]
	s_waitcnt vmcnt(8)
	v_pk_fma_f32 v[10:11], v[66:67], v[12:13], v[10:11] op_sel_hi:[1,0,1]
	v_mov_b32_e32 v12, v21
	v_pk_fma_f32 v[32:33], v[62:63], v[32:33], v[50:51] op_sel:[0,1,0]
	s_waitcnt lgkmcnt(0)
	v_pk_fma_f32 v[48:49], v[60:61], v[44:45], v[48:49] op_sel_hi:[1,0,1]
	v_pk_fma_f32 v[6:7], v[62:63], v[6:7], v[52:53] op_sel:[0,1,0]
	v_pk_fma_f32 v[30:31], v[62:63], v[36:37], v[68:69] op_sel:[0,1,0]
	v_pk_fma_f32 v[36:37], v[62:63], v[40:41], v[70:71] op_sel:[0,1,0]
	v_pk_fma_f32 v[40:41], v[62:63], v[44:45], v[48:49] op_sel:[0,1,0]
	v_pk_fma_f32 v[22:23], v[64:65], v[24:25], v[22:23] op_sel_hi:[1,0,1]
	v_pk_fma_f32 v[26:27], v[64:65], v[28:29], v[26:27] op_sel_hi:[1,0,1]
	v_pk_fma_f32 v[12:13], v[66:67], v[12:13], v[18:19] op_sel_hi:[1,0,1]
	v_mov_b32_e32 v18, v25
	v_mov_b32_e32 v20, v29
	v_pk_fma_f32 v[32:33], v[64:65], v[34:35], v[32:33] op_sel_hi:[1,0,1]
	v_pk_fma_f32 v[44:45], v[64:65], v[8:9], v[6:7] op_sel_hi:[1,0,1]
	v_pk_fma_f32 v[30:31], v[64:65], v[38:39], v[30:31] op_sel_hi:[1,0,1]
	v_pk_fma_f32 v[36:37], v[64:65], v[42:43], v[36:37] op_sel_hi:[1,0,1]
	v_pk_fma_f32 v[40:41], v[64:65], v[46:47], v[40:41] op_sel_hi:[1,0,1]
	v_mov_b32_e32 v6, v35
	v_mov_b32_e32 v8, v9
	v_pk_fma_f32 v[18:19], v[66:67], v[18:19], v[22:23] op_sel_hi:[1,0,1]
	v_pk_fma_f32 v[20:21], v[66:67], v[20:21], v[26:27] op_sel_hi:[1,0,1]
	v_mov_b32_e32 v22, v39
	v_mov_b32_e32 v24, v43
	v_mov_b32_e32 v26, v47
	v_pk_fma_f32 v[6:7], v[66:67], v[6:7], v[32:33] op_sel_hi:[1,0,1]
	v_pk_fma_f32 v[8:9], v[66:67], v[8:9], v[44:45] op_sel_hi:[1,0,1]
	v_pk_fma_f32 v[22:23], v[66:67], v[22:23], v[30:31] op_sel_hi:[1,0,1]
	v_pk_fma_f32 v[24:25], v[66:67], v[24:25], v[36:37] op_sel_hi:[1,0,1]
	v_pk_fma_f32 v[26:27], v[66:67], v[26:27], v[40:41] op_sel_hi:[1,0,1]
	v_lshl_add_u64 v[2:3], v[2:3], 0, s[54:55]
	v_add_co_u32_e32 v28, vcc, s28, v2
	s_nop 0
	v_addc_co_u32_e32 v29, vcc, -1, v3, vcc
	global_load_dwordx2 v[52:53], v[28:29], off nt
	v_add_co_u32_e32 v28, vcc, s29, v2
	s_nop 0
	v_addc_co_u32_e32 v29, vcc, -1, v3, vcc
	global_load_dwordx2 v[54:55], v[28:29], off nt
	v_add_co_u32_e32 v28, vcc, s22, v2
	s_nop 0
	v_addc_co_u32_e32 v29, vcc, -1, v3, vcc
	global_load_dwordx2 v[56:57], v[28:29], off nt
	v_add_co_u32_e32 v28, vcc, s23, v2
	s_nop 0
	v_addc_co_u32_e32 v29, vcc, -1, v3, vcc
	global_load_dwordx2 v[58:59], v[28:29], off nt
	v_add_co_u32_e32 v28, vcc, s26, v2
	s_nop 1
	v_addc_co_u32_e32 v29, vcc, -1, v3, vcc
	global_load_dwordx2 v[60:61], v[28:29], off nt
	v_add_co_u32_e32 v28, vcc, s27, v2
	s_nop 1
	v_addc_co_u32_e32 v29, vcc, -1, v3, vcc
	global_load_dwordx2 v[62:63], v[28:29], off nt
	v_add_co_u32_e32 v28, vcc, s95, v2
	s_nop 1
	v_addc_co_u32_e32 v29, vcc, -1, v3, vcc
	global_load_dwordx2 v[64:65], v[28:29], off nt
	global_load_dwordx2 v[66:67], v[2:3], off nt
	v_mov_b32_e32 v5, s6
	s_add_i32 s6, s6, 32
	ds_read_b128 v[28:31], v5
	ds_read_b128 v[32:35], v5 offset:16
	ds_read_b128 v[36:39], v5 offset:1024
	ds_read_b128 v[40:43], v5 offset:3072
	ds_read_b128 v[44:47], v5 offset:5120
	ds_read_b128 v[48:51], v5 offset:7168
	s_waitcnt vmcnt(15) lgkmcnt(5)
	v_pk_fma_f32 v[68:69], v[84:85], v[28:29], v[6:7] op_sel_hi:[1,0,1]
	s_waitcnt lgkmcnt(3)
	v_pk_fma_f32 v[70:71], v[84:85], v[36:37], v[8:9] op_sel_hi:[1,0,1]
	ds_read_b128 v[6:9], v5 offset:2048
	s_waitcnt lgkmcnt(3)
	v_pk_fma_f32 v[74:75], v[84:85], v[40:41], v[12:13] op_sel_hi:[1,0,1]
	s_waitcnt lgkmcnt(2)
	v_pk_fma_f32 v[78:79], v[84:85], v[44:45], v[20:21] op_sel_hi:[1,0,1]
	s_waitcnt lgkmcnt(1)
	v_pk_fma_f32 v[82:83], v[84:85], v[48:49], v[24:25] op_sel_hi:[1,0,1]
	s_waitcnt vmcnt(14)
	v_pk_fma_f32 v[28:29], v[86:87], v[28:29], v[68:69] op_sel:[0,1,0]
	s_waitcnt lgkmcnt(0)
	v_pk_fma_f32 v[72:73], v[84:85], v[6:7], v[10:11] op_sel_hi:[1,0,1]
	ds_read_b128 v[10:13], v5 offset:4096
	v_pk_fma_f32 v[6:7], v[86:87], v[6:7], v[72:73] op_sel:[0,1,0]
	v_pk_fma_f32 v[36:37], v[86:87], v[36:37], v[70:71] op_sel:[0,1,0]
	v_pk_fma_f32 v[40:41], v[86:87], v[40:41], v[74:75] op_sel:[0,1,0]
	s_waitcnt vmcnt(13)
	v_pk_fma_f32 v[6:7], v[88:89], v[8:9], v[6:7] op_sel_hi:[1,0,1]
	s_waitcnt lgkmcnt(0)
	v_pk_fma_f32 v[76:77], v[84:85], v[10:11], v[18:19] op_sel_hi:[1,0,1]
	ds_read_b128 v[18:21], v5 offset:6144
	v_mov_b32_e32 v8, v31
	v_pk_fma_f32 v[10:11], v[86:87], v[10:11], v[76:77] op_sel:[0,1,0]
	v_pk_fma_f32 v[44:45], v[86:87], v[44:45], v[78:79] op_sel:[0,1,0]
	v_pk_fma_f32 v[10:11], v[88:89], v[12:13], v[10:11] op_sel_hi:[1,0,1]
	s_waitcnt lgkmcnt(0)
	v_pk_fma_f32 v[80:81], v[84:85], v[18:19], v[22:23] op_sel_hi:[1,0,1]
	ds_read_b128 v[22:25], v5 offset:8192
	v_pk_fma_f32 v[18:19], v[86:87], v[18:19], v[80:81] op_sel:[0,1,0]
	v_pk_fma_f32 v[48:49], v[86:87], v[48:49], v[82:83] op_sel:[0,1,0]
	v_pk_fma_f32 v[18:19], v[88:89], v[20:21], v[18:19] op_sel_hi:[1,0,1]
	s_waitcnt lgkmcnt(0)
	v_pk_fma_f32 v[26:27], v[84:85], v[22:23], v[26:27] op_sel_hi:[1,0,1]
	s_nop 0
	v_pk_fma_f32 v[22:23], v[86:87], v[22:23], v[26:27] op_sel:[0,1,0]
	v_pk_fma_f32 v[26:27], v[88:89], v[30:31], v[28:29] op_sel_hi:[1,0,1]
	v_pk_fma_f32 v[28:29], v[88:89], v[38:39], v[36:37] op_sel_hi:[1,0,1]
	s_waitcnt vmcnt(12)
	v_pk_fma_f32 v[26:27], v[90:91], v[8:9], v[26:27] op_sel_hi:[1,0,1]
	v_mov_b32_e32 v8, v39
	v_pk_fma_f32 v[28:29], v[90:91], v[8:9], v[28:29] op_sel_hi:[1,0,1]
	v_mov_b32_e32 v8, v9
	v_pk_fma_f32 v[36:37], v[88:89], v[42:43], v[40:41] op_sel_hi:[1,0,1]
	v_pk_fma_f32 v[30:31], v[90:91], v[8:9], v[6:7] op_sel_hi:[1,0,1]
	v_mov_b32_e32 v6, v43
	v_pk_fma_f32 v[36:37], v[90:91], v[6:7], v[36:37] op_sel_hi:[1,0,1]
	v_mov_b32_e32 v6, v13
	v_pk_fma_f32 v[40:41], v[88:89], v[46:47], v[44:45] op_sel_hi:[1,0,1]
	v_pk_fma_f32 v[38:39], v[90:91], v[6:7], v[10:11] op_sel_hi:[1,0,1]
	v_mov_b32_e32 v6, v47
	v_pk_fma_f32 v[40:41], v[90:91], v[6:7], v[40:41] op_sel_hi:[1,0,1]
	v_mov_b32_e32 v6, v21
	v_pk_fma_f32 v[44:45], v[88:89], v[50:51], v[48:49] op_sel_hi:[1,0,1]
	v_pk_fma_f32 v[42:43], v[90:91], v[6:7], v[18:19] op_sel_hi:[1,0,1]
	v_mov_b32_e32 v6, v51
	v_pk_fma_f32 v[22:23], v[88:89], v[24:25], v[22:23] op_sel_hi:[1,0,1]
	v_pk_fma_f32 v[44:45], v[90:91], v[6:7], v[44:45] op_sel_hi:[1,0,1]
	v_mov_b32_e32 v6, v25
	v_pk_fma_f32 v[48:49], v[90:91], v[6:7], v[22:23] op_sel_hi:[1,0,1]
	ds_read_b128 v[6:9], v5 offset:1040
	ds_read_b128 v[10:13], v5 offset:2064
	ds_read_b128 v[18:21], v5 offset:3088
	ds_read_b128 v[22:25], v5 offset:4112
	s_waitcnt vmcnt(11)
	v_pk_fma_f32 v[50:51], v[92:93], v[32:33], v[26:27] op_sel_hi:[1,0,1]
	s_waitcnt lgkmcnt(3)
	v_pk_fma_f32 v[84:85], v[92:93], v[6:7], v[28:29] op_sel_hi:[1,0,1]
	ds_read_b128 v[26:29], v5 offset:5136
	s_waitcnt lgkmcnt(2)
	v_pk_fma_f32 v[86:87], v[92:93], v[18:19], v[36:37] op_sel_hi:[1,0,1]
	s_waitcnt lgkmcnt(1)
	v_pk_fma_f32 v[88:89], v[92:93], v[22:23], v[38:39] op_sel_hi:[1,0,1]
	ds_read_b128 v[36:39], v5 offset:6160
	v_pk_fma_f32 v[30:31], v[92:93], v[10:11], v[30:31] op_sel_hi:[1,0,1]
	s_waitcnt lgkmcnt(1)
	v_pk_fma_f32 v[90:91], v[92:93], v[26:27], v[40:41] op_sel_hi:[1,0,1]
	s_waitcnt vmcnt(10)
	v_pk_fma_f32 v[10:11], v[94:95], v[10:11], v[30:31] op_sel:[0,1,0]
	v_pk_fma_f32 v[18:19], v[94:95], v[18:19], v[86:87] op_sel:[0,1,0]
	s_waitcnt lgkmcnt(0)
	v_pk_fma_f32 v[68:69], v[92:93], v[36:37], v[42:43] op_sel_hi:[1,0,1]
	ds_read_b128 v[40:43], v5 offset:7184
	s_waitcnt vmcnt(9)
	v_pk_fma_f32 v[10:11], v[96:97], v[12:13], v[10:11] op_sel_hi:[1,0,1]
	v_mov_b32_e32 v12, v13
	v_pk_fma_f32 v[22:23], v[94:95], v[22:23], v[88:89] op_sel:[0,1,0]
	v_pk_fma_f32 v[26:27], v[94:95], v[26:27], v[90:91] op_sel:[0,1,0]
	s_waitcnt lgkmcnt(0)
	v_pk_fma_f32 v[70:71], v[92:93], v[40:41], v[44:45] op_sel_hi:[1,0,1]
	ds_read_b128 v[44:47], v5 offset:8208
	v_pk_fma_f32 v[18:19], v[96:97], v[20:21], v[18:19] op_sel_hi:[1,0,1]
	s_waitcnt vmcnt(8)
	v_pk_fma_f32 v[10:11], v[98:99], v[12:13], v[10:11] op_sel_hi:[1,0,1]
	v_mov_b32_e32 v12, v21
	v_pk_fma_f32 v[32:33], v[94:95], v[32:33], v[50:51] op_sel:[0,1,0]
	s_waitcnt lgkmcnt(0)
	v_pk_fma_f32 v[48:49], v[92:93], v[44:45], v[48:49] op_sel_hi:[1,0,1]
	v_pk_fma_f32 v[6:7], v[94:95], v[6:7], v[84:85] op_sel:[0,1,0]
	v_pk_fma_f32 v[30:31], v[94:95], v[36:37], v[68:69] op_sel:[0,1,0]
	v_pk_fma_f32 v[36:37], v[94:95], v[40:41], v[70:71] op_sel:[0,1,0]
	v_pk_fma_f32 v[40:41], v[94:95], v[44:45], v[48:49] op_sel:[0,1,0]
	v_pk_fma_f32 v[22:23], v[96:97], v[24:25], v[22:23] op_sel_hi:[1,0,1]
	v_pk_fma_f32 v[26:27], v[96:97], v[28:29], v[26:27] op_sel_hi:[1,0,1]
	v_pk_fma_f32 v[12:13], v[98:99], v[12:13], v[18:19] op_sel_hi:[1,0,1]
	v_mov_b32_e32 v18, v25
	v_mov_b32_e32 v20, v29
	v_pk_fma_f32 v[32:33], v[96:97], v[34:35], v[32:33] op_sel_hi:[1,0,1]
	v_pk_fma_f32 v[44:45], v[96:97], v[8:9], v[6:7] op_sel_hi:[1,0,1]
	v_pk_fma_f32 v[30:31], v[96:97], v[38:39], v[30:31] op_sel_hi:[1,0,1]
	v_pk_fma_f32 v[36:37], v[96:97], v[42:43], v[36:37] op_sel_hi:[1,0,1]
	v_pk_fma_f32 v[40:41], v[96:97], v[46:47], v[40:41] op_sel_hi:[1,0,1]
	v_mov_b32_e32 v6, v35
	v_mov_b32_e32 v8, v9
	v_pk_fma_f32 v[18:19], v[98:99], v[18:19], v[22:23] op_sel_hi:[1,0,1]
	v_pk_fma_f32 v[20:21], v[98:99], v[20:21], v[26:27] op_sel_hi:[1,0,1]
	v_mov_b32_e32 v22, v39
	v_mov_b32_e32 v24, v43
	v_mov_b32_e32 v26, v47
	v_pk_fma_f32 v[6:7], v[98:99], v[6:7], v[32:33] op_sel_hi:[1,0,1]
	v_pk_fma_f32 v[8:9], v[98:99], v[8:9], v[44:45] op_sel_hi:[1,0,1]
	v_pk_fma_f32 v[22:23], v[98:99], v[22:23], v[30:31] op_sel_hi:[1,0,1]
	v_pk_fma_f32 v[24:25], v[98:99], v[24:25], v[36:37] op_sel_hi:[1,0,1]
	v_pk_fma_f32 v[26:27], v[98:99], v[26:27], v[40:41] op_sel_hi:[1,0,1]
	s_add_i32 s3, s3, 16
	s_cmpk_lt_u32 s3, 0xe8
	s_cbranch_scc1 .LBB0_475
	v_lshl_add_u64 v[2:3], v[2:3], 0, s[54:55]
	v_add_co_u32_e32 v28, vcc, s28, v2
	s_nop 0
	v_addc_co_u32_e32 v29, vcc, -1, v3, vcc
	global_load_dwordx2 v[84:85], v[28:29], off nt
	v_add_co_u32_e32 v28, vcc, s29, v2
	s_nop 0
	v_addc_co_u32_e32 v29, vcc, -1, v3, vcc
	global_load_dwordx2 v[86:87], v[28:29], off nt
	v_add_co_u32_e32 v28, vcc, s22, v2
	s_nop 0
	v_addc_co_u32_e32 v29, vcc, -1, v3, vcc
	global_load_dwordx2 v[88:89], v[28:29], off nt
	v_add_co_u32_e32 v28, vcc, s23, v2
	s_nop 0
	v_addc_co_u32_e32 v29, vcc, -1, v3, vcc
	global_load_dwordx2 v[90:91], v[28:29], off nt
	v_add_co_u32_e32 v28, vcc, s26, v2
	s_nop 1
	v_addc_co_u32_e32 v29, vcc, -1, v3, vcc
	global_load_dwordx2 v[92:93], v[28:29], off nt
	v_add_co_u32_e32 v28, vcc, s27, v2
	s_nop 1
	v_addc_co_u32_e32 v29, vcc, -1, v3, vcc
	global_load_dwordx2 v[94:95], v[28:29], off nt
	v_add_co_u32_e32 v28, vcc, s95, v2
	s_nop 1
	v_addc_co_u32_e32 v29, vcc, -1, v3, vcc
	global_load_dwordx2 v[96:97], v[28:29], off nt
	global_load_dwordx2 v[98:99], v[2:3], off nt
	v_mov_b32_e32 v5, s6
	s_add_i32 s6, s6, 32
	ds_read_b128 v[28:31], v5
	ds_read_b128 v[32:35], v5 offset:16
	ds_read_b128 v[36:39], v5 offset:1024
	ds_read_b128 v[40:43], v5 offset:3072
	ds_read_b128 v[44:47], v5 offset:5120
	ds_read_b128 v[48:51], v5 offset:7168
	s_waitcnt vmcnt(15) lgkmcnt(5)
	v_pk_fma_f32 v[68:69], v[52:53], v[28:29], v[6:7] op_sel_hi:[1,0,1]
	s_waitcnt lgkmcnt(3)
	v_pk_fma_f32 v[70:71], v[52:53], v[36:37], v[8:9] op_sel_hi:[1,0,1]
	ds_read_b128 v[6:9], v5 offset:2048
	s_waitcnt lgkmcnt(3)
	v_pk_fma_f32 v[74:75], v[52:53], v[40:41], v[12:13] op_sel_hi:[1,0,1]
	s_waitcnt lgkmcnt(2)
	v_pk_fma_f32 v[78:79], v[52:53], v[44:45], v[20:21] op_sel_hi:[1,0,1]
	s_waitcnt lgkmcnt(1)
	v_pk_fma_f32 v[82:83], v[52:53], v[48:49], v[24:25] op_sel_hi:[1,0,1]
	s_waitcnt vmcnt(14)
	v_pk_fma_f32 v[28:29], v[54:55], v[28:29], v[68:69] op_sel:[0,1,0]
	s_waitcnt lgkmcnt(0)
	v_pk_fma_f32 v[72:73], v[52:53], v[6:7], v[10:11] op_sel_hi:[1,0,1]
	ds_read_b128 v[10:13], v5 offset:4096
	v_pk_fma_f32 v[6:7], v[54:55], v[6:7], v[72:73] op_sel:[0,1,0]
	v_pk_fma_f32 v[36:37], v[54:55], v[36:37], v[70:71] op_sel:[0,1,0]
	v_pk_fma_f32 v[40:41], v[54:55], v[40:41], v[74:75] op_sel:[0,1,0]
	s_waitcnt vmcnt(13)
	v_pk_fma_f32 v[6:7], v[56:57], v[8:9], v[6:7] op_sel_hi:[1,0,1]
	s_waitcnt lgkmcnt(0)
	v_pk_fma_f32 v[76:77], v[52:53], v[10:11], v[18:19] op_sel_hi:[1,0,1]
	ds_read_b128 v[18:21], v5 offset:6144
	v_mov_b32_e32 v8, v31
	v_pk_fma_f32 v[10:11], v[54:55], v[10:11], v[76:77] op_sel:[0,1,0]
	v_pk_fma_f32 v[44:45], v[54:55], v[44:45], v[78:79] op_sel:[0,1,0]
	v_pk_fma_f32 v[10:11], v[56:57], v[12:13], v[10:11] op_sel_hi:[1,0,1]
	s_waitcnt lgkmcnt(0)
	v_pk_fma_f32 v[80:81], v[52:53], v[18:19], v[22:23] op_sel_hi:[1,0,1]
	ds_read_b128 v[22:25], v5 offset:8192
	v_pk_fma_f32 v[18:19], v[54:55], v[18:19], v[80:81] op_sel:[0,1,0]
	v_pk_fma_f32 v[48:49], v[54:55], v[48:49], v[82:83] op_sel:[0,1,0]
	v_pk_fma_f32 v[18:19], v[56:57], v[20:21], v[18:19] op_sel_hi:[1,0,1]
	s_waitcnt lgkmcnt(0)
	v_pk_fma_f32 v[26:27], v[52:53], v[22:23], v[26:27] op_sel_hi:[1,0,1]
	s_nop 0
	v_pk_fma_f32 v[22:23], v[54:55], v[22:23], v[26:27] op_sel:[0,1,0]
	v_pk_fma_f32 v[26:27], v[56:57], v[30:31], v[28:29] op_sel_hi:[1,0,1]
	v_pk_fma_f32 v[28:29], v[56:57], v[38:39], v[36:37] op_sel_hi:[1,0,1]
	s_waitcnt vmcnt(12)
	v_pk_fma_f32 v[26:27], v[58:59], v[8:9], v[26:27] op_sel_hi:[1,0,1]
	v_mov_b32_e32 v8, v39
	v_pk_fma_f32 v[28:29], v[58:59], v[8:9], v[28:29] op_sel_hi:[1,0,1]
	v_mov_b32_e32 v8, v9
	v_pk_fma_f32 v[36:37], v[56:57], v[42:43], v[40:41] op_sel_hi:[1,0,1]
	v_pk_fma_f32 v[30:31], v[58:59], v[8:9], v[6:7] op_sel_hi:[1,0,1]
	v_mov_b32_e32 v6, v43
	v_pk_fma_f32 v[36:37], v[58:59], v[6:7], v[36:37] op_sel_hi:[1,0,1]
	v_mov_b32_e32 v6, v13
	v_pk_fma_f32 v[40:41], v[56:57], v[46:47], v[44:45] op_sel_hi:[1,0,1]
	v_pk_fma_f32 v[38:39], v[58:59], v[6:7], v[10:11] op_sel_hi:[1,0,1]
	v_mov_b32_e32 v6, v47
	v_pk_fma_f32 v[40:41], v[58:59], v[6:7], v[40:41] op_sel_hi:[1,0,1]
	v_mov_b32_e32 v6, v21
	v_pk_fma_f32 v[44:45], v[56:57], v[50:51], v[48:49] op_sel_hi:[1,0,1]
	v_pk_fma_f32 v[42:43], v[58:59], v[6:7], v[18:19] op_sel_hi:[1,0,1]
	v_mov_b32_e32 v6, v51
	v_pk_fma_f32 v[22:23], v[56:57], v[24:25], v[22:23] op_sel_hi:[1,0,1]
	v_pk_fma_f32 v[44:45], v[58:59], v[6:7], v[44:45] op_sel_hi:[1,0,1]
	v_mov_b32_e32 v6, v25
	v_pk_fma_f32 v[48:49], v[58:59], v[6:7], v[22:23] op_sel_hi:[1,0,1]
	ds_read_b128 v[6:9], v5 offset:1040
	ds_read_b128 v[10:13], v5 offset:2064
	ds_read_b128 v[18:21], v5 offset:3088
	ds_read_b128 v[22:25], v5 offset:4112
	s_waitcnt vmcnt(11)
	v_pk_fma_f32 v[50:51], v[60:61], v[32:33], v[26:27] op_sel_hi:[1,0,1]
	s_waitcnt lgkmcnt(3)
	v_pk_fma_f32 v[52:53], v[60:61], v[6:7], v[28:29] op_sel_hi:[1,0,1]
	ds_read_b128 v[26:29], v5 offset:5136
	s_waitcnt lgkmcnt(2)
	v_pk_fma_f32 v[54:55], v[60:61], v[18:19], v[36:37] op_sel_hi:[1,0,1]
	s_waitcnt lgkmcnt(1)
	v_pk_fma_f32 v[56:57], v[60:61], v[22:23], v[38:39] op_sel_hi:[1,0,1]
	ds_read_b128 v[36:39], v5 offset:6160
	v_pk_fma_f32 v[30:31], v[60:61], v[10:11], v[30:31] op_sel_hi:[1,0,1]
	s_waitcnt lgkmcnt(1)
	v_pk_fma_f32 v[58:59], v[60:61], v[26:27], v[40:41] op_sel_hi:[1,0,1]
	s_waitcnt vmcnt(10)
	v_pk_fma_f32 v[10:11], v[62:63], v[10:11], v[30:31] op_sel:[0,1,0]
	v_pk_fma_f32 v[18:19], v[62:63], v[18:19], v[54:55] op_sel:[0,1,0]
	s_waitcnt lgkmcnt(0)
	v_pk_fma_f32 v[68:69], v[60:61], v[36:37], v[42:43] op_sel_hi:[1,0,1]
	ds_read_b128 v[40:43], v5 offset:7184
	s_waitcnt vmcnt(9)
	v_pk_fma_f32 v[10:11], v[64:65], v[12:13], v[10:11] op_sel_hi:[1,0,1]
	v_mov_b32_e32 v12, v13
	v_pk_fma_f32 v[22:23], v[62:63], v[22:23], v[56:57] op_sel:[0,1,0]
	v_pk_fma_f32 v[26:27], v[62:63], v[26:27], v[58:59] op_sel:[0,1,0]
	s_waitcnt lgkmcnt(0)
	v_pk_fma_f32 v[70:71], v[60:61], v[40:41], v[44:45] op_sel_hi:[1,0,1]
	ds_read_b128 v[44:47], v5 offset:8208
	v_pk_fma_f32 v[18:19], v[64:65], v[20:21], v[18:19] op_sel_hi:[1,0,1]
	s_waitcnt vmcnt(8)
	v_pk_fma_f32 v[10:11], v[66:67], v[12:13], v[10:11] op_sel_hi:[1,0,1]
	v_mov_b32_e32 v12, v21
	v_pk_fma_f32 v[32:33], v[62:63], v[32:33], v[50:51] op_sel:[0,1,0]
	s_waitcnt lgkmcnt(0)
	v_pk_fma_f32 v[48:49], v[60:61], v[44:45], v[48:49] op_sel_hi:[1,0,1]
	v_pk_fma_f32 v[6:7], v[62:63], v[6:7], v[52:53] op_sel:[0,1,0]
	v_pk_fma_f32 v[30:31], v[62:63], v[36:37], v[68:69] op_sel:[0,1,0]
	v_pk_fma_f32 v[36:37], v[62:63], v[40:41], v[70:71] op_sel:[0,1,0]
	v_pk_fma_f32 v[40:41], v[62:63], v[44:45], v[48:49] op_sel:[0,1,0]
	v_pk_fma_f32 v[22:23], v[64:65], v[24:25], v[22:23] op_sel_hi:[1,0,1]
	v_pk_fma_f32 v[26:27], v[64:65], v[28:29], v[26:27] op_sel_hi:[1,0,1]
	v_pk_fma_f32 v[12:13], v[66:67], v[12:13], v[18:19] op_sel_hi:[1,0,1]
	v_mov_b32_e32 v18, v25
	v_mov_b32_e32 v20, v29
	v_pk_fma_f32 v[32:33], v[64:65], v[34:35], v[32:33] op_sel_hi:[1,0,1]
	v_pk_fma_f32 v[44:45], v[64:65], v[8:9], v[6:7] op_sel_hi:[1,0,1]
	v_pk_fma_f32 v[30:31], v[64:65], v[38:39], v[30:31] op_sel_hi:[1,0,1]
	v_pk_fma_f32 v[36:37], v[64:65], v[42:43], v[36:37] op_sel_hi:[1,0,1]
	v_pk_fma_f32 v[40:41], v[64:65], v[46:47], v[40:41] op_sel_hi:[1,0,1]
	v_mov_b32_e32 v6, v35
	v_mov_b32_e32 v8, v9
	v_pk_fma_f32 v[18:19], v[66:67], v[18:19], v[22:23] op_sel_hi:[1,0,1]
	v_pk_fma_f32 v[20:21], v[66:67], v[20:21], v[26:27] op_sel_hi:[1,0,1]
	v_mov_b32_e32 v22, v39
	v_mov_b32_e32 v24, v43
	v_mov_b32_e32 v26, v47
	v_pk_fma_f32 v[6:7], v[66:67], v[6:7], v[32:33] op_sel_hi:[1,0,1]
	v_pk_fma_f32 v[8:9], v[66:67], v[8:9], v[44:45] op_sel_hi:[1,0,1]
	v_pk_fma_f32 v[22:23], v[66:67], v[22:23], v[30:31] op_sel_hi:[1,0,1]
	v_pk_fma_f32 v[24:25], v[66:67], v[24:25], v[36:37] op_sel_hi:[1,0,1]
	v_pk_fma_f32 v[26:27], v[66:67], v[26:27], v[40:41] op_sel_hi:[1,0,1]
	v_mov_b32_e32 v5, s6
	s_add_i32 s6, s6, 32
	ds_read_b128 v[28:31], v5
	ds_read_b128 v[32:35], v5 offset:16
	ds_read_b128 v[36:39], v5 offset:1024
	ds_read_b128 v[40:43], v5 offset:3072
	ds_read_b128 v[44:47], v5 offset:5120
	ds_read_b128 v[48:51], v5 offset:7168
	s_waitcnt vmcnt(7) lgkmcnt(5)
	v_pk_fma_f32 v[68:69], v[84:85], v[28:29], v[6:7] op_sel_hi:[1,0,1]
	s_waitcnt lgkmcnt(3)
	v_pk_fma_f32 v[70:71], v[84:85], v[36:37], v[8:9] op_sel_hi:[1,0,1]
	ds_read_b128 v[6:9], v5 offset:2048
	s_waitcnt lgkmcnt(3)
	v_pk_fma_f32 v[74:75], v[84:85], v[40:41], v[12:13] op_sel_hi:[1,0,1]
	s_waitcnt lgkmcnt(2)
	v_pk_fma_f32 v[78:79], v[84:85], v[44:45], v[20:21] op_sel_hi:[1,0,1]
	s_waitcnt lgkmcnt(1)
	v_pk_fma_f32 v[82:83], v[84:85], v[48:49], v[24:25] op_sel_hi:[1,0,1]
	s_waitcnt vmcnt(6)
	v_pk_fma_f32 v[28:29], v[86:87], v[28:29], v[68:69] op_sel:[0,1,0]
	s_waitcnt lgkmcnt(0)
	v_pk_fma_f32 v[72:73], v[84:85], v[6:7], v[10:11] op_sel_hi:[1,0,1]
	ds_read_b128 v[10:13], v5 offset:4096
	v_pk_fma_f32 v[6:7], v[86:87], v[6:7], v[72:73] op_sel:[0,1,0]
	v_pk_fma_f32 v[36:37], v[86:87], v[36:37], v[70:71] op_sel:[0,1,0]
	v_pk_fma_f32 v[40:41], v[86:87], v[40:41], v[74:75] op_sel:[0,1,0]
	s_waitcnt vmcnt(5)
	v_pk_fma_f32 v[6:7], v[88:89], v[8:9], v[6:7] op_sel_hi:[1,0,1]
	s_waitcnt lgkmcnt(0)
	v_pk_fma_f32 v[76:77], v[84:85], v[10:11], v[18:19] op_sel_hi:[1,0,1]
	ds_read_b128 v[18:21], v5 offset:6144
	v_mov_b32_e32 v8, v31
	v_pk_fma_f32 v[10:11], v[86:87], v[10:11], v[76:77] op_sel:[0,1,0]
	v_pk_fma_f32 v[44:45], v[86:87], v[44:45], v[78:79] op_sel:[0,1,0]
	v_pk_fma_f32 v[10:11], v[88:89], v[12:13], v[10:11] op_sel_hi:[1,0,1]
	s_waitcnt lgkmcnt(0)
	v_pk_fma_f32 v[80:81], v[84:85], v[18:19], v[22:23] op_sel_hi:[1,0,1]
	ds_read_b128 v[22:25], v5 offset:8192
	v_pk_fma_f32 v[18:19], v[86:87], v[18:19], v[80:81] op_sel:[0,1,0]
	v_pk_fma_f32 v[48:49], v[86:87], v[48:49], v[82:83] op_sel:[0,1,0]
	v_pk_fma_f32 v[18:19], v[88:89], v[20:21], v[18:19] op_sel_hi:[1,0,1]
	s_waitcnt lgkmcnt(0)
	v_pk_fma_f32 v[26:27], v[84:85], v[22:23], v[26:27] op_sel_hi:[1,0,1]
	s_nop 0
	v_pk_fma_f32 v[22:23], v[86:87], v[22:23], v[26:27] op_sel:[0,1,0]
	v_pk_fma_f32 v[26:27], v[88:89], v[30:31], v[28:29] op_sel_hi:[1,0,1]
	v_pk_fma_f32 v[28:29], v[88:89], v[38:39], v[36:37] op_sel_hi:[1,0,1]
	s_waitcnt vmcnt(4)
	v_pk_fma_f32 v[26:27], v[90:91], v[8:9], v[26:27] op_sel_hi:[1,0,1]
	v_mov_b32_e32 v8, v39
	v_pk_fma_f32 v[28:29], v[90:91], v[8:9], v[28:29] op_sel_hi:[1,0,1]
	v_mov_b32_e32 v8, v9
	v_pk_fma_f32 v[36:37], v[88:89], v[42:43], v[40:41] op_sel_hi:[1,0,1]
	v_pk_fma_f32 v[30:31], v[90:91], v[8:9], v[6:7] op_sel_hi:[1,0,1]
	v_mov_b32_e32 v6, v43
	v_pk_fma_f32 v[36:37], v[90:91], v[6:7], v[36:37] op_sel_hi:[1,0,1]
	v_mov_b32_e32 v6, v13
	v_pk_fma_f32 v[40:41], v[88:89], v[46:47], v[44:45] op_sel_hi:[1,0,1]
	v_pk_fma_f32 v[38:39], v[90:91], v[6:7], v[10:11] op_sel_hi:[1,0,1]
	v_mov_b32_e32 v6, v47
	v_pk_fma_f32 v[40:41], v[90:91], v[6:7], v[40:41] op_sel_hi:[1,0,1]
	v_mov_b32_e32 v6, v21
	v_pk_fma_f32 v[44:45], v[88:89], v[50:51], v[48:49] op_sel_hi:[1,0,1]
	v_pk_fma_f32 v[42:43], v[90:91], v[6:7], v[18:19] op_sel_hi:[1,0,1]
	v_mov_b32_e32 v6, v51
	v_pk_fma_f32 v[22:23], v[88:89], v[24:25], v[22:23] op_sel_hi:[1,0,1]
	v_pk_fma_f32 v[44:45], v[90:91], v[6:7], v[44:45] op_sel_hi:[1,0,1]
	v_mov_b32_e32 v6, v25
	v_pk_fma_f32 v[48:49], v[90:91], v[6:7], v[22:23] op_sel_hi:[1,0,1]
	ds_read_b128 v[6:9], v5 offset:1040
	ds_read_b128 v[10:13], v5 offset:2064
	ds_read_b128 v[18:21], v5 offset:3088
	ds_read_b128 v[22:25], v5 offset:4112
	s_waitcnt vmcnt(3)
	v_pk_fma_f32 v[50:51], v[92:93], v[32:33], v[26:27] op_sel_hi:[1,0,1]
	s_waitcnt lgkmcnt(3)
	v_pk_fma_f32 v[84:85], v[92:93], v[6:7], v[28:29] op_sel_hi:[1,0,1]
	ds_read_b128 v[26:29], v5 offset:5136
	s_waitcnt lgkmcnt(2)
	v_pk_fma_f32 v[86:87], v[92:93], v[18:19], v[36:37] op_sel_hi:[1,0,1]
	s_waitcnt lgkmcnt(1)
	v_pk_fma_f32 v[88:89], v[92:93], v[22:23], v[38:39] op_sel_hi:[1,0,1]
	ds_read_b128 v[36:39], v5 offset:6160
	v_pk_fma_f32 v[30:31], v[92:93], v[10:11], v[30:31] op_sel_hi:[1,0,1]
	s_waitcnt lgkmcnt(1)
	v_pk_fma_f32 v[90:91], v[92:93], v[26:27], v[40:41] op_sel_hi:[1,0,1]
	s_waitcnt vmcnt(2)
	v_pk_fma_f32 v[10:11], v[94:95], v[10:11], v[30:31] op_sel:[0,1,0]
	v_pk_fma_f32 v[18:19], v[94:95], v[18:19], v[86:87] op_sel:[0,1,0]
	s_waitcnt lgkmcnt(0)
	v_pk_fma_f32 v[68:69], v[92:93], v[36:37], v[42:43] op_sel_hi:[1,0,1]
	ds_read_b128 v[40:43], v5 offset:7184
	s_waitcnt vmcnt(1)
	v_pk_fma_f32 v[10:11], v[96:97], v[12:13], v[10:11] op_sel_hi:[1,0,1]
	v_mov_b32_e32 v12, v13
	v_pk_fma_f32 v[22:23], v[94:95], v[22:23], v[88:89] op_sel:[0,1,0]
	v_pk_fma_f32 v[26:27], v[94:95], v[26:27], v[90:91] op_sel:[0,1,0]
	s_waitcnt lgkmcnt(0)
	v_pk_fma_f32 v[70:71], v[92:93], v[40:41], v[44:45] op_sel_hi:[1,0,1]
	ds_read_b128 v[44:47], v5 offset:8208
	v_pk_fma_f32 v[18:19], v[96:97], v[20:21], v[18:19] op_sel_hi:[1,0,1]
	s_waitcnt vmcnt(0)
	v_pk_fma_f32 v[10:11], v[98:99], v[12:13], v[10:11] op_sel_hi:[1,0,1]
	v_mov_b32_e32 v12, v21
	v_pk_fma_f32 v[32:33], v[94:95], v[32:33], v[50:51] op_sel:[0,1,0]
	s_waitcnt lgkmcnt(0)
	v_pk_fma_f32 v[48:49], v[92:93], v[44:45], v[48:49] op_sel_hi:[1,0,1]
	v_pk_fma_f32 v[6:7], v[94:95], v[6:7], v[84:85] op_sel:[0,1,0]
	v_pk_fma_f32 v[30:31], v[94:95], v[36:37], v[68:69] op_sel:[0,1,0]
	v_pk_fma_f32 v[36:37], v[94:95], v[40:41], v[70:71] op_sel:[0,1,0]
	v_pk_fma_f32 v[40:41], v[94:95], v[44:45], v[48:49] op_sel:[0,1,0]
	v_pk_fma_f32 v[22:23], v[96:97], v[24:25], v[22:23] op_sel_hi:[1,0,1]
	v_pk_fma_f32 v[26:27], v[96:97], v[28:29], v[26:27] op_sel_hi:[1,0,1]
	v_pk_fma_f32 v[12:13], v[98:99], v[12:13], v[18:19] op_sel_hi:[1,0,1]
	v_mov_b32_e32 v18, v25
	v_mov_b32_e32 v20, v29
	v_pk_fma_f32 v[32:33], v[96:97], v[34:35], v[32:33] op_sel_hi:[1,0,1]
	v_pk_fma_f32 v[44:45], v[96:97], v[8:9], v[6:7] op_sel_hi:[1,0,1]
	v_pk_fma_f32 v[30:31], v[96:97], v[38:39], v[30:31] op_sel_hi:[1,0,1]
	v_pk_fma_f32 v[36:37], v[96:97], v[42:43], v[36:37] op_sel_hi:[1,0,1]
	v_pk_fma_f32 v[40:41], v[96:97], v[46:47], v[40:41] op_sel_hi:[1,0,1]
	v_mov_b32_e32 v6, v35
	v_mov_b32_e32 v8, v9
	v_pk_fma_f32 v[18:19], v[98:99], v[18:19], v[22:23] op_sel_hi:[1,0,1]
	v_pk_fma_f32 v[20:21], v[98:99], v[20:21], v[26:27] op_sel_hi:[1,0,1]
	v_mov_b32_e32 v22, v39
	v_mov_b32_e32 v24, v43
	v_mov_b32_e32 v26, v47
	v_pk_fma_f32 v[6:7], v[98:99], v[6:7], v[32:33] op_sel_hi:[1,0,1]
	v_pk_fma_f32 v[8:9], v[98:99], v[8:9], v[44:45] op_sel_hi:[1,0,1]
	v_pk_fma_f32 v[22:23], v[98:99], v[22:23], v[30:31] op_sel_hi:[1,0,1]
	v_pk_fma_f32 v[24:25], v[98:99], v[24:25], v[36:37] op_sel_hi:[1,0,1]
	v_pk_fma_f32 v[26:27], v[98:99], v[26:27], v[40:41] op_sel_hi:[1,0,1]
	s_waitcnt lgkmcnt(0)
	v_add_u32_e32 v2, s34, v0
	ds_write2st64_b64 v2, v[6:7], v[8:9] offset1:1
	ds_write2st64_b64 v2, v[10:11], v[12:13] offset0:2 offset1:3
	ds_write2st64_b64 v2, v[18:19], v[20:21] offset0:4 offset1:5
	ds_write2st64_b64 v2, v[22:23], v[24:25] offset0:6 offset1:7
	ds_write_b64 v2, v[26:27] offset:4096
	s_waitcnt lgkmcnt(0)
	s_cmp_gt_i32 s43, 8
	s_waitcnt lgkmcnt(0)
	s_barrier
	s_cbranch_scc1 .LBB0_479
	s_load_dwordx2 s[6:7], s[58:59], 0x30
	s_mul_i32 s8, s0, 0xc000
	s_mul_hi_i32 s3, s0, 0xc000
	v_mov_b32_e32 v2, v0
	v_mov_b32_e32 v3, v4
	s_waitcnt lgkmcnt(0)
	s_add_u32 s6, s6, s8
	s_addc_u32 s3, s7, s3
	s_add_u32 s6, s6, s4
	s_addc_u32 s7, s3, s5
	v_lshl_add_u64 v[2:3], s[6:7], 0, v[2:3]
	s_add_i32 s3, s43, -8
	s_mul_hi_i32 s6, s0, 0x6c000
	s_mul_i32 s0, s0, 0x6c000
	s_mul_i32 s8, s43, 0xc000
	s_mul_hi_i32 s7, s43, 0xc000
	s_add_u32 s0, s0, s8
	s_addc_u32 s6, s6, s7
	s_add_u32 s4, s92, s4
	s_addc_u32 s5, s24, s5
	s_add_u32 s4, s4, s0
	s_addc_u32 s5, s5, s6
	s_lshl_b32 s0, s43, 9
	s_add_i32 s0, s0, 0
	s_add_i32 s0, s0, 0x10000
	v_lshl_add_u64 v[6:7], s[4:5], 0, v[0:1]
	v_add_u32_e32 v0, s0, v0
